# P3 mid-K gate hook aligned like the epilogue: leading half takes one extra barrier before the hook, trailing half one after it, so both halves run the hook concurrently instead of back to back
# baseline (speedup 1.0000x reference)
; #define UNPK0(q_) ((f32x4){bf_lo((q_).x), bf_hi((q_).x), bf_lo((q_).y), bf_hi((q_).y)})
;     __device__ __forceinline__ void mid(f32x4 (&acc)[2][2][4][2], const Unit& u, int wr, int wc, int fr, int fq) const {
;         int pm = u.pm, cb = u.pn * 4 + wc;
;         asm volatile("" : "+v"(pm), "+v"(cb));
;         const PieceIn pa(scr, Z, tm_block(pm, ga_ct + cb, znct), wr, wc, fr, fq), pb(scr, Z, tm_block(pm, gb_ct + cb, znct), wr, wc, fr, fq);
;         const int col0 = cb * 64 + 8 * fq;
;         f32x4 ba[2][2], bb[2][2];
; #pragma unroll
;         for (int bj = 0; bj < 2; ++bj) { ba[bj][0] = *(const f32x4*)(bg + col0 + bj * 32); ba[bj][1] = *(const f32x4*)(bg + col0 + bj * 32 + 4); bb[bj][0] = *(const f32x4*)(bg + 1024 + col0 + bj * 32); bb[bj][1] = *(const f32x4*)(bg + 1024 + col0 + bj * 32 + 4); }
; #pragma unroll
;         for (int am = 0; am < 4; ++am) { const int ai = am >> 1;
;             u32x4 ra[4][2], rb[4][2];
; #pragma unroll
;             for (int m = 2 * (am & 1); m < 2 * (am & 1) + 2; ++m) { pa.fetch(ai, m, ra[m][0], ra[m][1]); pb.fetch(ai, m, rb[m][0], rb[m][1]); }
;             asm volatile("" ::: "memory");
; #pragma unroll
;             for (int m = 2 * (am & 1); m < 2 * (am & 1) + 2; ++m) {
;                 pa.stage(ra[m][0], ra[m][1]); const u32x4 ga0 = pa.get(0), ga1 = pa.get(1);
;                 asm volatile("" ::: "memory");
;                 pb.stage(rb[m][0], rb[m][1]); const u32x4 gb0 = pb.get(0), gb1 = pb.get(1);
;                 asm volatile("" ::: "memory");
; #pragma unroll
;                 for (int bj = 0; bj < 2; ++bj) { const u32x4 ga = bj ? ga1 : ga0, gb = bj ? gb1 : gb0;
;                     const f32x4 a0 = UNPK0(ga) + ba[bj][0], a1 = UNPK1(ga) + ba[bj][1], b0 = UNPK0(gb) + bb[bj][0], b1 = UNPK1(gb) + bb[bj][1];
; #pragma unroll
;                     for (int k = 0; k < 4; ++k) { acc[ai][bj][m][0][k] *= (1.0f + eneg(b0[k])) * __builtin_amdgcn_rcpf(1.0f + eneg(a0[k]));
;                                                   acc[ai][bj][m][1][k] *= (1.0f + eneg(b1[k])) * __builtin_amdgcn_rcpf(1.0f + eneg(a1[k])); } } }
; template <class Epi, class Sched, bool ALIGN_EPI = false, bool SP2 = false>
; __device__ __forceinline__ void gemm_phase(PG8_LAS unsigned char* lds, const Gemm g, const Sched& S, const Epi& E) {
;     ...
;             if constexpr (Epi::HAS_MID) { if (t == (nt >> 1)) E.mid(acc, cur, wr, wc, fr, fq); }
.LBB0_381:
	s_cmp_lg_u32 s46, 0x40000
	s_cbranch_scc1 .LBB0_380
	s_bitcmp1_b32 s14, 0
	s_cbranch_scc0 .Lp3_mid_nox
	s_barrier
.Lp3_mid_nox:
	v_mov_b32_e32 v3, s26
	v_mov_b32_e32 v136, s44
	v_add_u32_e32 v188, v223, v220
	v_add_u32_e32 v4, 36, v136
	v_ashrrev_i32_e32 v5, 31, v4
	v_mad_i64_i32 v[4:5], s[48:49], v3, s83, v[4:5]
	v_add_u32_e32 v134, 52, v136
	v_ashrrev_i32_e32 v135, 31, v134
	v_lshlrev_b64 v[4:5], 15, v[4:5]
	v_lshl_add_u64 v[186:187], v[208:209], 0, v[4:5]
	v_mad_i64_i32 v[4:5], s[48:49], v3, s83, v[134:135]
	global_load_dwordx4 v[190:193], v[186:187], off
	global_load_dwordx4 v[194:197], v[186:187], off offset:1024
	v_lshlrev_b64 v[4:5], 15, v[4:5]
	v_lshl_add_u64 v[4:5], v[208:209], 0, v[4:5]
	global_load_dwordx4 v[228:231], v[4:5], off
	global_load_dwordx4 v[232:235], v[4:5], off offset:1024
	v_lshl_or_b32 v134, v136, 6, v219
	v_ashrrev_i32_e32 v135, 31, v134
	v_lshlrev_b64 v[134:135], 2, v[134:135]
	v_lshl_add_u64 v[138:139], s[42:43], 0, v[134:135]
	v_add_co_u32_e32 v166, vcc, s84, v138
	v_lshl_add_u64 v[140:141], s[16:17], 0, v[134:135]
	global_load_dwordx4 v[150:153], v[138:139], off offset:16
	global_load_dwordx4 v[158:161], v[138:139], off
	global_load_dwordx4 v[162:165], v[140:141], off
	v_addc_co_u32_e32 v167, vcc, 0, v139, vcc
	global_load_dwordx4 v[154:157], v[166:167], off offset:16
	global_load_dwordx4 v[134:137], v[138:139], off offset:144
	global_load_dwordx4 v[142:145], v[138:139], off offset:128
	global_load_dwordx4 v[146:149], v[140:141], off offset:128
	s_nop 0
	global_load_dwordx4 v[138:141], v[166:167], off offset:144
	global_load_dwordx4 v[174:177], v[186:187], off offset:2048
	global_load_dwordx4 v[178:181], v[186:187], off offset:3072
	s_nop 0
	global_load_dwordx4 v[166:169], v[4:5], off offset:2048
	global_load_dwordx4 v[170:173], v[4:5], off offset:3072
	v_add_u32_e32 v3, v224, v222
	s_waitcnt vmcnt(0)
	ds_write_b128 v3, v[190:193]
	ds_write_b128 v3, v[194:197] offset:1152
	ds_read_b128 v[190:193], v188
	ds_read_b128 v[194:197], v188 offset:64
	ds_write_b128 v3, v[228:231]
	ds_write_b128 v3, v[232:235] offset:1152
	ds_read_b128 v[228:231], v188
	ds_read_b128 v[232:235], v188 offset:64
	s_waitcnt lgkmcnt(0)
	v_lshlrev_b32_e32 v189, 16, v190
	v_and_b32_e32 v190, 0xffff0000, v190
	v_lshlrev_b32_e32 v227, 16, v191
	v_and_b32_e32 v237, 0xffff0000, v191
	v_lshlrev_b32_e32 v191, 16, v192
	v_add_f32_e32 v189, v158, v189
	v_and_b32_e32 v192, 0xffff0000, v192
	v_lshlrev_b32_e32 v239, 16, v193
	v_and_b32_e32 v241, 0xffff0000, v193
	v_lshlrev_b32_e32 v193, 16, v228
	v_and_b32_e32 v228, 0xffff0000, v228
	v_lshlrev_b32_e32 v236, 16, v229
	v_and_b32_e32 v242, 0xffff0000, v229
	v_lshlrev_b32_e32 v229, 16, v230
	v_add_f32_e32 v191, v150, v191
	v_add_f32_e32 v190, v159, v190
	v_med3_f32 v189, v189, s85, v226
	v_add_f32_e32 v192, v151, v192
	v_add_f32_e32 v193, v162, v193
	v_add_f32_e32 v229, v154, v229
	v_med3_f32 v191, v191, s85, v226
	v_add_f32_e32 v228, v163, v228
	v_med3_f32 v190, v190, s85, v226
	v_mul_f32_e32 v189, 0xbfb8aa3b, v189
	v_med3_f32 v192, v192, s85, v226
	v_med3_f32 v193, v193, s85, v226
	v_med3_f32 v229, v229, s85, v226
	v_mul_f32_e32 v191, 0xbfb8aa3b, v191
	v_med3_f32 v228, v228, s85, v226
	v_mul_f32_e32 v190, 0xbfb8aa3b, v190
	v_exp_f32_e32 v189, v189
	v_mul_f32_e32 v238, 0xbfb8aa3b, v192
	v_mul_f32_e32 v192, 0xbfb8aa3b, v193
	v_mul_f32_e32 v193, 0xbfb8aa3b, v229
	v_exp_f32_e32 v229, v191
	v_mul_f32_e32 v191, 0xbfb8aa3b, v228
	v_exp_f32_e32 v228, v190
	v_add_f32_e32 v189, 1.0, v189
	v_exp_f32_e32 v190, v192
	v_exp_f32_e32 v192, v193
	v_add_f32_e32 v193, 1.0, v229
	v_add_f32_e32 v229, 1.0, v228
	v_rcp_f32_e32 v228, v189
	v_exp_f32_e32 v189, v238
	v_add_f32_e32 v227, v160, v227
	v_med3_f32 v227, v227, s85, v226
	v_and_b32_e32 v230, 0xffff0000, v230
	v_mul_f32_e32 v227, 0xbfb8aa3b, v227
	v_lshlrev_b32_e32 v240, 16, v231
	v_and_b32_e32 v243, 0xffff0000, v231
	v_add_f32_e32 v231, v155, v230
	v_add_f32_e32 v189, 1.0, v189
	v_exp_f32_e32 v227, v227
	v_rcp_f32_e32 v230, v193
	v_med3_f32 v193, v231, s85, v226
	v_rcp_f32_e32 v231, v189
	v_add_f32_e32 v189, v164, v236
	v_med3_f32 v189, v189, s85, v226
	v_mul_f32_e32 v189, 0xbfb8aa3b, v189
	v_exp_f32_e32 v236, v189
	v_add_f32_e32 v189, 1.0, v227
	v_add_f32_e32 v227, v152, v239
	v_med3_f32 v227, v227, s85, v226
	v_mul_f32_e32 v227, 0xbfb8aa3b, v227
	v_exp_f32_e32 v227, v227
	v_rcp_f32_e32 v238, v189
	v_add_f32_e32 v189, v156, v240
	v_med3_f32 v189, v189, s85, v226
	v_mul_f32_e32 v189, 0xbfb8aa3b, v189
	v_add_f32_e32 v237, v161, v237
	v_exp_f32_e32 v240, v189
	v_add_f32_e32 v189, 1.0, v227
	v_add_f32_e32 v227, v165, v242
	v_med3_f32 v237, v237, s85, v226
	v_med3_f32 v227, v227, s85, v226
	v_mul_f32_e32 v237, 0xbfb8aa3b, v237
	v_exp_f32_e32 v239, v237
	v_mul_f32_e32 v227, 0xbfb8aa3b, v227
	v_exp_f32_e32 v237, v227
	v_add_f32_e32 v227, v153, v241
	v_med3_f32 v227, v227, s85, v226
	v_mul_f32_e32 v227, 0xbfb8aa3b, v227
	v_rcp_f32_e32 v242, v189
	v_add_f32_e32 v189, 1.0, v239
	v_exp_f32_e32 v227, v227
	v_rcp_f32_e32 v239, v189
	v_add_f32_e32 v189, v157, v243
	v_mul_f32_e32 v193, 0xbfb8aa3b, v193
	v_med3_f32 v189, v189, s85, v226
	v_exp_f32_e32 v193, v193
	v_mul_f32_e32 v189, 0xbfb8aa3b, v189
	v_exp_f32_e32 v241, v189
	v_add_f32_e32 v189, 1.0, v227
	v_exp_f32_e32 v191, v191
	v_rcp_f32_e32 v243, v189
	v_lshlrev_b32_e32 v189, 16, v194
	v_rcp_f32_e32 v229, v229
	v_add_f32_e32 v189, v142, v189
	v_pk_add_f32 v[192:193], v[192:193], 1.0 op_sel_hi:[1,0]
	v_med3_f32 v189, v189, s85, v226
	v_pk_mul_f32 v[192:193], v[230:231], v[192:193]
	v_mul_f32_e32 v189, 0xbfb8aa3b, v189
	v_pk_add_f32 v[190:191], v[190:191], 1.0 op_sel_hi:[1,0]
	v_pk_mul_f32 v[126:127], v[126:127], v[192:193]
; #define UNPK0(q_) ((f32x4){bf_lo((q_).x), bf_hi((q_).x), bf_lo((q_).y), bf_hi((q_).y)})
; #define UNPK1(q_) ((f32x4){bf_lo((q_).z), bf_hi((q_).z), bf_lo((q_).w), bf_hi((q_).w)})
;     static __device__ __forceinline__ float eneg(float g) { return __builtin_amdgcn_exp2f(-1.4426950408889634f * fminf(fmaxf(g, -30.f), 30.f)); }
;     __device__ __forceinline__ void mid(f32x4 (&acc)[2][2][4][2], const Unit& u, int wr, int wc, int fr, int fq) const {
;     ...
;             for (int m = 2 * (am & 1); m < 2 * (am & 1) + 2; ++m) {
;                 pa.stage(ra[m][0], ra[m][1]); const u32x4 ga0 = pa.get(0), ga1 = pa.get(1);
;                 asm volatile("" ::: "memory");
;                 pb.stage(rb[m][0], rb[m][1]); const u32x4 gb0 = pb.get(0), gb1 = pb.get(1);
;                 asm volatile("" ::: "memory");
; #pragma unroll
;                 for (int bj = 0; bj < 2; ++bj) { const u32x4 ga = bj ? ga1 : ga0, gb = bj ? gb1 : gb0;
;                     const f32x4 a0 = UNPK0(ga) + ba[bj][0], a1 = UNPK1(ga) + ba[bj][1], b0 = UNPK0(gb) + bb[bj][0], b1 = UNPK1(gb) + bb[bj][1];
; #pragma unroll
;                     for (int k = 0; k < 4; ++k) { acc[ai][bj][m][0][k] *= (1.0f + eneg(b0[k])) * __builtin_amdgcn_rcpf(1.0f + eneg(a0[k]));
;                                                   acc[ai][bj][m][1][k] *= (1.0f + eneg(b1[k])) * __builtin_amdgcn_rcpf(1.0f + eneg(a1[k])); } } }
	v_lshlrev_b32_e32 v193, 16, v196
	v_exp_f32_e32 v189, v189
	v_pk_mul_f32 v[190:191], v[228:229], v[190:191]
	v_add_f32_e32 v193, v134, v193
	v_pk_mul_f32 v[130:131], v[130:131], v[190:191]
	v_pk_add_f32 v[190:191], v[240:241], 1.0 op_sel_hi:[1,0]
	v_med3_f32 v193, v193, s85, v226
	v_pk_mul_f32 v[190:191], v[242:243], v[190:191]
	v_mul_f32_e32 v193, 0xbfb8aa3b, v193
	v_pk_mul_f32 v[128:129], v[128:129], v[190:191]
	v_and_b32_e32 v191, 0xffff0000, v194
	v_lshlrev_b32_e32 v194, 16, v234
	v_add_f32_e32 v189, 1.0, v189
	v_exp_f32_e32 v193, v193
	v_rcp_f32_e32 v192, v189
	v_add_f32_e32 v189, v138, v194
	v_add_f32_e32 v191, v143, v191
	v_pk_add_f32 v[236:237], v[236:237], 1.0 op_sel_hi:[1,0]
	v_med3_f32 v189, v189, s85, v226
	v_med3_f32 v191, v191, s85, v226
	v_pk_mul_f32 v[228:229], v[238:239], v[236:237]
	v_mul_f32_e32 v189, 0xbfb8aa3b, v189
	v_mul_f32_e32 v191, 0xbfb8aa3b, v191
	v_pk_mul_f32 v[132:133], v[132:133], v[228:229]
	v_lshlrev_b32_e32 v227, 16, v195
	v_and_b32_e32 v229, 0xffff0000, v195
	v_and_b32_e32 v195, 0xffff0000, v196
	v_lshlrev_b32_e32 v231, 16, v197
	v_and_b32_e32 v236, 0xffff0000, v197
	v_and_b32_e32 v197, 0xffff0000, v232
	v_exp_f32_e32 v194, v189
	v_add_f32_e32 v189, 1.0, v193
	v_exp_f32_e32 v193, v191
	v_rcp_f32_e32 v196, v189
	v_add_f32_e32 v189, v147, v197
	v_add_f32_e32 v195, v135, v195
	v_med3_f32 v189, v189, s85, v226
	v_med3_f32 v195, v195, s85, v226
	v_mul_f32_e32 v189, 0xbfb8aa3b, v189
	v_mul_f32_e32 v195, 0xbfb8aa3b, v195
	v_and_b32_e32 v230, 0xffff0000, v234
	v_exp_f32_e32 v191, v189
	v_add_f32_e32 v189, 1.0, v193
	v_exp_f32_e32 v197, v195
	v_rcp_f32_e32 v193, v189
	v_add_f32_e32 v189, v139, v230
	v_add_f32_e32 v227, v144, v227
	v_med3_f32 v189, v189, s85, v226
	v_med3_f32 v227, v227, s85, v226
	v_mul_f32_e32 v189, 0xbfb8aa3b, v189
	v_mul_f32_e32 v227, 0xbfb8aa3b, v227
	v_lshlrev_b32_e32 v228, 16, v233
	v_exp_f32_e32 v195, v189
	v_add_f32_e32 v189, 1.0, v197
	v_exp_f32_e32 v227, v227
	v_rcp_f32_e32 v197, v189
	v_add_f32_e32 v189, v148, v228
	v_med3_f32 v189, v189, s85, v226
	v_mul_f32_e32 v189, 0xbfb8aa3b, v189
	v_exp_f32_e32 v228, v189
	v_add_f32_e32 v189, 1.0, v227
	v_add_f32_e32 v227, v136, v231
	v_med3_f32 v227, v227, s85, v226
	v_mul_f32_e32 v227, 0xbfb8aa3b, v227
	v_lshlrev_b32_e32 v190, 16, v232
	v_lshlrev_b32_e32 v232, 16, v235
	v_exp_f32_e32 v227, v227
	v_add_f32_e32 v229, v145, v229
	v_rcp_f32_e32 v230, v189
	v_add_f32_e32 v189, v140, v232
	v_med3_f32 v229, v229, s85, v226
	v_med3_f32 v189, v189, s85, v226
	v_mul_f32_e32 v229, 0xbfb8aa3b, v229
	v_and_b32_e32 v233, 0xffff0000, v233
	v_mul_f32_e32 v189, 0xbfb8aa3b, v189
	v_exp_f32_e32 v231, v229
	v_add_f32_e32 v190, v146, v190
	v_exp_f32_e32 v232, v189
	v_add_f32_e32 v189, 1.0, v227
	v_add_f32_e32 v227, v149, v233
	v_med3_f32 v190, v190, s85, v226
	v_med3_f32 v227, v227, s85, v226
	v_mul_f32_e32 v190, 0xbfb8aa3b, v190
	v_mul_f32_e32 v227, 0xbfb8aa3b, v227
	v_exp_f32_e32 v190, v190
	v_exp_f32_e32 v229, v227
	v_rcp_f32_e32 v234, v189
	v_add_f32_e32 v189, 1.0, v231
	v_rcp_f32_e32 v231, v189
	v_pk_add_f32 v[228:229], v[228:229], 1.0 op_sel_hi:[1,0]
	v_pk_add_f32 v[190:191], v[190:191], 1.0 op_sel_hi:[1,0]
	v_and_b32_e32 v235, 0xffff0000, v235
	v_pk_mul_f32 v[190:191], v[192:193], v[190:191]
	v_pk_mul_f32 v[192:193], v[230:231], v[228:229]
	v_add_f32_e32 v189, v141, v235
	v_pk_mul_f32 v[124:125], v[124:125], v[192:193]
	v_add_f32_e32 v192, v137, v236
	v_med3_f32 v192, v192, s85, v226
	v_mul_f32_e32 v192, 0xbfb8aa3b, v192
	v_exp_f32_e32 v192, v192
	v_med3_f32 v189, v189, s85, v226
	v_mul_f32_e32 v189, 0xbfb8aa3b, v189
	v_exp_f32_e32 v233, v189
	v_add_f32_e32 v189, 1.0, v192
	v_rcp_f32_e32 v235, v189
	ds_write_b128 v3, v[174:177]
	ds_write_b128 v3, v[178:181] offset:1152
	ds_read_b128 v[174:177], v188
	ds_read_b128 v[178:181], v188 offset:64
	ds_write_b128 v3, v[166:169]
	ds_write_b128 v3, v[170:173] offset:1152
	ds_read_b128 v[166:169], v188
	ds_read_b128 v[170:173], v188 offset:64
	v_pk_mul_f32 v[122:123], v[122:123], v[190:191]
	v_pk_add_f32 v[190:191], v[232:233], 1.0 op_sel_hi:[1,0]
	s_waitcnt lgkmcnt(5)
	v_lshlrev_b32_e32 v189, 16, v174
	v_pk_mul_f32 v[190:191], v[234:235], v[190:191]
	s_waitcnt lgkmcnt(1)
	v_lshlrev_b32_e32 v227, 16, v169
	v_pk_mul_f32 v[120:121], v[120:121], v[190:191]
	v_and_b32_e32 v190, 0xffff0000, v174
	v_lshlrev_b32_e32 v174, 16, v176
	v_and_b32_e32 v228, 0xffff0000, v169
	v_add_f32_e32 v169, v150, v174
	v_pk_add_f32 v[192:193], v[194:195], 1.0 op_sel_hi:[1,0]
	v_med3_f32 v169, v169, s85, v226
	v_pk_mul_f32 v[192:193], v[196:197], v[192:193]
	v_mul_f32_e32 v169, 0xbfb8aa3b, v169
	v_pk_mul_f32 v[118:119], v[118:119], v[192:193]
	v_lshlrev_b32_e32 v191, 16, v175
	v_and_b32_e32 v193, 0xffff0000, v175
	v_and_b32_e32 v175, 0xffff0000, v176
	v_lshlrev_b32_e32 v192, 16, v167
	v_and_b32_e32 v196, 0xffff0000, v167
	v_lshlrev_b32_e32 v167, 16, v168
	v_exp_f32_e32 v169, v169
	v_add_f32_e32 v167, v154, v167
	v_add_f32_e32 v175, v151, v175
	v_med3_f32 v167, v167, s85, v226
	v_med3_f32 v175, v175, s85, v226
	v_mul_f32_e32 v167, 0xbfb8aa3b, v167
	v_mul_f32_e32 v175, 0xbfb8aa3b, v175
	v_and_b32_e32 v197, 0xffff0000, v168
	v_add_f32_e32 v168, v158, v189
	v_exp_f32_e32 v174, v167
	v_add_f32_e32 v167, 1.0, v169
	v_add_f32_e32 v169, v159, v190
	v_exp_f32_e32 v189, v175
	v_add_f32_e32 v190, v160, v191
	v_med3_f32 v190, v190, s85, v226
	v_lshlrev_b32_e32 v194, 16, v177
	v_and_b32_e32 v195, 0xffff0000, v177
	v_lshlrev_b32_e32 v176, 16, v166
	v_and_b32_e32 v177, 0xffff0000, v166
	v_mul_f32_e32 v190, 0xbfb8aa3b, v190
	v_add_f32_e32 v166, v162, v176
	v_rcp_f32_e32 v176, v167
	v_add_f32_e32 v167, v163, v177
	v_add_f32_e32 v177, v155, v197
; #define UNPK0(q_) ((f32x4){bf_lo((q_).x), bf_hi((q_).x), bf_lo((q_).y), bf_hi((q_).y)})
; #define UNPK1(q_) ((f32x4){bf_lo((q_).z), bf_hi((q_).z), bf_lo((q_).w), bf_hi((q_).w)})
;     static __device__ __forceinline__ float eneg(float g) { return __builtin_amdgcn_exp2f(-1.4426950408889634f * fminf(fmaxf(g, -30.f), 30.f)); }
;     __device__ __forceinline__ void mid(f32x4 (&acc)[2][2][4][2], const Unit& u, int wr, int wc, int fr, int fq) const {
;     ...
;         for (int am = 0; am < 4; ++am) { const int ai = am >> 1;
;             u32x4 ra[4][2], rb[4][2];
; #pragma unroll
;             for (int m = 2 * (am & 1); m < 2 * (am & 1) + 2; ++m) { pa.fetch(ai, m, ra[m][0], ra[m][1]); pb.fetch(ai, m, rb[m][0], rb[m][1]); }
;             asm volatile("" ::: "memory");
; #pragma unroll
;             for (int m = 2 * (am & 1); m < 2 * (am & 1) + 2; ++m) {
;                 pa.stage(ra[m][0], ra[m][1]); const u32x4 ga0 = pa.get(0), ga1 = pa.get(1);
;                 asm volatile("" ::: "memory");
;                 pb.stage(rb[m][0], rb[m][1]); const u32x4 gb0 = pb.get(0), gb1 = pb.get(1);
;                 asm volatile("" ::: "memory");
; #pragma unroll
;                 for (int bj = 0; bj < 2; ++bj) { const u32x4 ga = bj ? ga1 : ga0, gb = bj ? gb1 : gb0;
;                     const f32x4 a0 = UNPK0(ga) + ba[bj][0], a1 = UNPK1(ga) + ba[bj][1], b0 = UNPK0(gb) + bb[bj][0], b1 = UNPK1(gb) + bb[bj][1];
; #pragma unroll
;                     for (int k = 0; k < 4; ++k) { acc[ai][bj][m][0][k] *= (1.0f + eneg(b0[k])) * __builtin_amdgcn_rcpf(1.0f + eneg(a0[k]));
;                                                   acc[ai][bj][m][1][k] *= (1.0f + eneg(b1[k])) * __builtin_amdgcn_rcpf(1.0f + eneg(a1[k])); } } }
	v_exp_f32_e32 v191, v190
	v_med3_f32 v175, v177, s85, v226
	v_add_f32_e32 v177, 1.0, v189
	v_add_f32_e32 v189, v164, v192
	v_med3_f32 v189, v189, s85, v226
	v_mul_f32_e32 v189, 0xbfb8aa3b, v189
	v_exp_f32_e32 v190, v189
	v_add_f32_e32 v189, 1.0, v191
	v_add_f32_e32 v191, v152, v194
	v_med3_f32 v191, v191, s85, v226
	v_mul_f32_e32 v191, 0xbfb8aa3b, v191
	v_exp_f32_e32 v191, v191
	v_add_f32_e32 v193, v161, v193
	v_med3_f32 v168, v168, s85, v226
	v_med3_f32 v169, v169, s85, v226
	v_rcp_f32_e32 v192, v189
	v_add_f32_e32 v189, v156, v227
	v_med3_f32 v193, v193, s85, v226
	v_mul_f32_e32 v168, 0xbfb8aa3b, v168
	v_mul_f32_e32 v169, 0xbfb8aa3b, v169
	v_med3_f32 v189, v189, s85, v226
	v_mul_f32_e32 v193, 0xbfb8aa3b, v193
	v_exp_f32_e32 v168, v168
	v_exp_f32_e32 v169, v169
	v_mul_f32_e32 v189, 0xbfb8aa3b, v189
	v_exp_f32_e32 v193, v193
	v_exp_f32_e32 v194, v189
	v_add_f32_e32 v189, 1.0, v191
	v_add_f32_e32 v191, v165, v196
	v_med3_f32 v166, v166, s85, v226
	v_med3_f32 v167, v167, s85, v226
	v_med3_f32 v191, v191, s85, v226
	v_mul_f32_e32 v166, 0xbfb8aa3b, v166
	v_mul_f32_e32 v167, 0xbfb8aa3b, v167
	v_mul_f32_e32 v191, 0xbfb8aa3b, v191
	v_exp_f32_e32 v166, v166
	v_add_f32_e32 v168, 1.0, v168
	v_exp_f32_e32 v167, v167
	v_add_f32_e32 v169, 1.0, v169
	v_exp_f32_e32 v191, v191
	v_rcp_f32_e32 v196, v189
	v_add_f32_e32 v189, 1.0, v193
	v_rcp_f32_e32 v168, v168
	v_rcp_f32_e32 v169, v169
	v_rcp_f32_e32 v193, v189
	v_pk_add_f32 v[190:191], v[190:191], 1.0 op_sel_hi:[1,0]
	v_pk_add_f32 v[166:167], v[166:167], 1.0 op_sel_hi:[1,0]
	v_mul_f32_e32 v175, 0xbfb8aa3b, v175
	v_pk_mul_f32 v[166:167], v[168:169], v[166:167]
	v_pk_mul_f32 v[168:169], v[192:193], v[190:191]
	v_exp_f32_e32 v175, v175
	v_pk_mul_f32 v[116:117], v[116:117], v[168:169]
	v_add_f32_e32 v169, v153, v195
	v_med3_f32 v169, v169, s85, v226
	v_mul_f32_e32 v169, 0xbfb8aa3b, v169
	v_exp_f32_e32 v169, v169
	v_add_f32_e32 v168, v157, v228
	v_med3_f32 v168, v168, s85, v226
	v_mul_f32_e32 v168, 0xbfb8aa3b, v168
	v_rcp_f32_e32 v177, v177
	v_exp_f32_e32 v195, v168
	v_pk_mul_f32 v[114:115], v[114:115], v[166:167]
	v_add_f32_e32 v166, 1.0, v169
	v_rcp_f32_e32 v197, v166
	v_pk_add_f32 v[168:169], v[174:175], 1.0 op_sel_hi:[1,0]
	v_pk_add_f32 v[166:167], v[194:195], 1.0 op_sel_hi:[1,0]
	v_pk_mul_f32 v[168:169], v[176:177], v[168:169]
	v_pk_mul_f32 v[166:167], v[196:197], v[166:167]
	v_pk_mul_f32 v[110:111], v[110:111], v[168:169]
	v_lshlrev_b32_e32 v169, 16, v180
	v_pk_mul_f32 v[112:113], v[112:113], v[166:167]
	v_lshlrev_b32_e32 v166, 16, v178
	v_add_f32_e32 v169, v134, v169
	v_add_f32_e32 v166, v142, v166
	v_med3_f32 v169, v169, s85, v226
	v_med3_f32 v166, v166, s85, v226
	v_mul_f32_e32 v169, 0xbfb8aa3b, v169
	v_mul_f32_e32 v166, 0xbfb8aa3b, v166
	v_exp_f32_e32 v169, v169
	v_and_b32_e32 v167, 0xffff0000, v178
	v_and_b32_e32 v176, 0xffff0000, v180
	s_waitcnt lgkmcnt(0)
	v_lshlrev_b32_e32 v168, 16, v170
	v_and_b32_e32 v178, 0xffff0000, v170
	v_lshlrev_b32_e32 v180, 16, v171
	v_and_b32_e32 v189, 0xffff0000, v171
	v_lshlrev_b32_e32 v170, 16, v172
	v_and_b32_e32 v171, 0xffff0000, v172
	v_exp_f32_e32 v172, v166
	v_add_f32_e32 v168, v146, v168
	v_add_f32_e32 v169, 1.0, v169
	v_med3_f32 v166, v168, s85, v226
	v_add_f32_e32 v168, 1.0, v172
	v_rcp_f32_e32 v172, v169
	v_add_f32_e32 v169, v147, v178
	v_add_co_u32_e32 v178, vcc, s84, v186
	v_lshlrev_b32_e32 v174, 16, v179
	v_and_b32_e32 v175, 0xffff0000, v179
	v_addc_co_u32_e32 v179, vcc, 0, v187, vcc
	global_load_dwordx4 v[190:193], v[178:179], off
	global_load_dwordx4 v[194:197], v[178:179], off offset:1024
	v_add_co_u32_e32 v236, vcc, s84, v4
	v_add_f32_e32 v167, v143, v167
	s_nop 0
	v_addc_co_u32_e32 v237, vcc, 0, v5, vcc
	global_load_dwordx4 v[228:231], v[236:237], off
	global_load_dwordx4 v[232:235], v[236:237], off offset:1024
	v_med3_f32 v167, v167, s85, v226
	v_mul_f32_e32 v167, 0xbfb8aa3b, v167
	v_lshlrev_b32_e32 v227, 16, v173
	v_and_b32_e32 v239, 0xffff0000, v173
	v_exp_f32_e32 v173, v167
	v_add_f32_e32 v174, v144, v174
	v_med3_f32 v174, v174, s85, v226
	v_lshlrev_b32_e32 v177, 16, v181
	v_mul_f32_e32 v174, 0xbfb8aa3b, v174
	v_med3_f32 v167, v169, s85, v226
	v_add_f32_e32 v169, 1.0, v173
	v_add_f32_e32 v173, v135, v176
	v_add_f32_e32 v176, v148, v180
	v_exp_f32_e32 v180, v174
	v_add_f32_e32 v177, v136, v177
	v_med3_f32 v177, v177, s85, v226
	v_add_f32_e32 v175, v145, v175
	v_mul_f32_e32 v177, 0xbfb8aa3b, v177
	v_med3_f32 v175, v175, s85, v226
	v_exp_f32_e32 v177, v177
	v_mul_f32_e32 v175, 0xbfb8aa3b, v175
	v_med3_f32 v174, v176, s85, v226
	v_add_f32_e32 v176, 1.0, v180
	v_add_f32_e32 v180, v140, v227
	v_exp_f32_e32 v227, v175
	v_add_f32_e32 v189, v149, v189
	v_med3_f32 v189, v189, s85, v226
	v_mul_f32_e32 v166, 0xbfb8aa3b, v166
	v_mul_f32_e32 v167, 0xbfb8aa3b, v167
	v_mul_f32_e32 v174, 0xbfb8aa3b, v174
	v_add_f32_e32 v177, 1.0, v177
	v_mul_f32_e32 v175, 0xbfb8aa3b, v189
	v_exp_f32_e32 v166, v166
	v_exp_f32_e32 v167, v167
	v_exp_f32_e32 v174, v174
	v_exp_f32_e32 v175, v175
	v_rcp_f32_e32 v238, v177
	v_add_f32_e32 v177, 1.0, v227
	v_rcp_f32_e32 v168, v168
	v_rcp_f32_e32 v169, v169
	v_rcp_f32_e32 v176, v176
	v_rcp_f32_e32 v177, v177
	v_pk_add_f32 v[174:175], v[174:175], 1.0 op_sel_hi:[1,0]
	v_pk_add_f32 v[166:167], v[166:167], 1.0 op_sel_hi:[1,0]
	v_and_b32_e32 v181, 0xffff0000, v181
	v_pk_mul_f32 v[166:167], v[168:169], v[166:167]
	v_pk_mul_f32 v[168:169], v[176:177], v[174:175]
	v_med3_f32 v173, v173, s85, v226
	v_pk_mul_f32 v[108:109], v[108:109], v[168:169]
	v_add_f32_e32 v169, v137, v181
	v_med3_f32 v169, v169, s85, v226
	v_mul_f32_e32 v173, 0xbfb8aa3b, v173
	v_mul_f32_e32 v169, 0xbfb8aa3b, v169
	v_exp_f32_e32 v173, v173
	v_exp_f32_e32 v169, v169
	v_add_f32_e32 v170, v138, v170
	v_add_f32_e32 v171, v139, v171
	v_add_f32_e32 v168, v141, v239
	v_med3_f32 v170, v170, s85, v226
	v_med3_f32 v171, v171, s85, v226
	v_med3_f32 v180, v180, s85, v226
	v_med3_f32 v168, v168, s85, v226
	v_mul_f32_e32 v170, 0xbfb8aa3b, v170
	v_mul_f32_e32 v171, 0xbfb8aa3b, v171
	v_mul_f32_e32 v180, 0xbfb8aa3b, v180
	v_mul_f32_e32 v168, 0xbfb8aa3b, v168
	v_exp_f32_e32 v170, v170
	v_exp_f32_e32 v171, v171
	v_add_f32_e32 v173, 1.0, v173
	v_exp_f32_e32 v180, v180
	v_exp_f32_e32 v181, v168
	v_pk_mul_f32 v[106:107], v[106:107], v[166:167]
	v_add_f32_e32 v166, 1.0, v169
	v_rcp_f32_e32 v173, v173
	v_rcp_f32_e32 v239, v166
	v_pk_add_f32 v[166:167], v[180:181], 1.0 op_sel_hi:[1,0]
	v_pk_add_f32 v[168:169], v[170:171], 1.0 op_sel_hi:[1,0]
	v_pk_mul_f32 v[166:167], v[238:239], v[166:167]
	v_pk_mul_f32 v[168:169], v[172:173], v[168:169]
	v_pk_mul_f32 v[104:105], v[104:105], v[166:167]
	v_pk_mul_f32 v[102:103], v[102:103], v[168:169]
	global_load_dwordx4 v[174:177], v[178:179], off offset:2048
	s_nop 0
	global_load_dwordx4 v[178:181], v[178:179], off offset:3072
	s_nop 0
	global_load_dwordx4 v[166:169], v[236:237], off offset:2048
	global_load_dwordx4 v[170:173], v[236:237], off offset:3072
	s_waitcnt vmcnt(7)
; #define UNPK0(q_) ((f32x4){bf_lo((q_).x), bf_hi((q_).x), bf_lo((q_).y), bf_hi((q_).y)})
; #define UNPK1(q_) ((f32x4){bf_lo((q_).z), bf_hi((q_).z), bf_lo((q_).w), bf_hi((q_).w)})
;     static __device__ __forceinline__ float eneg(float g) { return __builtin_amdgcn_exp2f(-1.4426950408889634f * fminf(fmaxf(g, -30.f), 30.f)); }
;     __device__ __forceinline__ void mid(f32x4 (&acc)[2][2][4][2], const Unit& u, int wr, int wc, int fr, int fq) const {
;     ...
;             for (int m = 2 * (am & 1); m < 2 * (am & 1) + 2; ++m) {
;                 pa.stage(ra[m][0], ra[m][1]); const u32x4 ga0 = pa.get(0), ga1 = pa.get(1);
;                 asm volatile("" ::: "memory");
;                 pb.stage(rb[m][0], rb[m][1]); const u32x4 gb0 = pb.get(0), gb1 = pb.get(1);
;                 asm volatile("" ::: "memory");
; #pragma unroll
;                 for (int bj = 0; bj < 2; ++bj) { const u32x4 ga = bj ? ga1 : ga0, gb = bj ? gb1 : gb0;
;                     const f32x4 a0 = UNPK0(ga) + ba[bj][0], a1 = UNPK1(ga) + ba[bj][1], b0 = UNPK0(gb) + bb[bj][0], b1 = UNPK1(gb) + bb[bj][1];
; #pragma unroll
;                     for (int k = 0; k < 4; ++k) { acc[ai][bj][m][0][k] *= (1.0f + eneg(b0[k])) * __builtin_amdgcn_rcpf(1.0f + eneg(a0[k]));
;                                                   acc[ai][bj][m][1][k] *= (1.0f + eneg(b1[k])) * __builtin_amdgcn_rcpf(1.0f + eneg(a1[k])); } } }
	ds_write_b128 v3, v[190:193]
	s_waitcnt vmcnt(6)
	ds_write_b128 v3, v[194:197] offset:1152
	ds_read_b128 v[190:193], v188
	ds_read_b128 v[194:197], v188 offset:64
	s_waitcnt vmcnt(5)
	ds_write_b128 v3, v[228:231]
	s_waitcnt vmcnt(4)
	ds_write_b128 v3, v[232:235] offset:1152
	ds_read_b128 v[228:231], v188
	ds_read_b128 v[232:235], v188 offset:64
	s_waitcnt lgkmcnt(5)
	v_lshlrev_b32_e32 v189, 16, v190
	v_add_f32_e32 v189, v158, v189
	v_med3_f32 v189, v189, s85, v226
	v_mul_f32_e32 v189, 0xbfb8aa3b, v189
	v_lshlrev_b32_e32 v236, 16, v191
	v_and_b32_e32 v237, 0xffff0000, v191
	v_lshlrev_b32_e32 v191, 16, v192
	v_exp_f32_e32 v189, v189
	v_add_f32_e32 v191, v150, v191
	v_med3_f32 v191, v191, s85, v226
	v_mul_f32_e32 v191, 0xbfb8aa3b, v191
	v_and_b32_e32 v227, 0xffff0000, v190
	v_lshlrev_b32_e32 v239, 16, v193
	v_and_b32_e32 v241, 0xffff0000, v193
	s_waitcnt lgkmcnt(1)
	v_lshlrev_b32_e32 v190, 16, v228
	v_and_b32_e32 v193, 0xffff0000, v228
	v_lshlrev_b32_e32 v228, 16, v230
	v_add_f32_e32 v189, 1.0, v189
	v_exp_f32_e32 v191, v191
	v_and_b32_e32 v238, 0xffff0000, v192
	v_rcp_f32_e32 v192, v189
	v_add_f32_e32 v189, v154, v228
	v_med3_f32 v189, v189, s85, v226
	v_mul_f32_e32 v189, 0xbfb8aa3b, v189
	v_exp_f32_e32 v228, v189
	v_add_f32_e32 v189, 1.0, v191
	v_add_f32_e32 v191, v159, v227
	v_med3_f32 v191, v191, s85, v226
	v_mul_f32_e32 v191, 0xbfb8aa3b, v191
	v_lshlrev_b32_e32 v240, 16, v229
	v_and_b32_e32 v242, 0xffff0000, v229
	v_and_b32_e32 v229, 0xffff0000, v230
	v_rcp_f32_e32 v230, v189
	v_add_f32_e32 v189, v163, v193
	v_exp_f32_e32 v193, v191
	v_add_f32_e32 v227, v151, v238
	v_med3_f32 v189, v189, s85, v226
	v_med3_f32 v227, v227, s85, v226
	v_mul_f32_e32 v189, 0xbfb8aa3b, v189
	v_mul_f32_e32 v227, 0xbfb8aa3b, v227
	v_exp_f32_e32 v191, v189
	v_add_f32_e32 v189, 1.0, v193
	v_exp_f32_e32 v227, v227
	v_rcp_f32_e32 v193, v189
	v_add_f32_e32 v189, v155, v229
	v_med3_f32 v189, v189, s85, v226
	v_mul_f32_e32 v189, 0xbfb8aa3b, v189
	v_exp_f32_e32 v229, v189
	v_add_f32_e32 v189, 1.0, v227
	v_add_f32_e32 v227, v160, v236
	v_med3_f32 v227, v227, s85, v226
	v_mul_f32_e32 v227, 0xbfb8aa3b, v227
	v_exp_f32_e32 v227, v227
	v_lshlrev_b32_e32 v243, 16, v231
	v_and_b32_e32 v244, 0xffff0000, v231
	v_rcp_f32_e32 v231, v189
	v_add_f32_e32 v189, v164, v240
	v_med3_f32 v189, v189, s85, v226
	v_mul_f32_e32 v189, 0xbfb8aa3b, v189
	v_exp_f32_e32 v236, v189
	v_add_f32_e32 v189, 1.0, v227
	v_add_f32_e32 v227, v152, v239
	v_med3_f32 v227, v227, s85, v226
	v_mul_f32_e32 v227, 0xbfb8aa3b, v227
	v_exp_f32_e32 v227, v227
	v_add_f32_e32 v237, v161, v237
	v_rcp_f32_e32 v238, v189
	v_add_f32_e32 v189, v156, v243
	v_med3_f32 v237, v237, s85, v226
	v_med3_f32 v189, v189, s85, v226
	v_mul_f32_e32 v237, 0xbfb8aa3b, v237
	v_mul_f32_e32 v189, 0xbfb8aa3b, v189
	v_exp_f32_e32 v239, v237
	v_add_f32_e32 v190, v162, v190
	v_exp_f32_e32 v240, v189
	v_add_f32_e32 v189, 1.0, v227
	v_add_f32_e32 v227, v165, v242
	v_med3_f32 v190, v190, s85, v226
	v_med3_f32 v227, v227, s85, v226
	v_mul_f32_e32 v190, 0xbfb8aa3b, v190
	v_mul_f32_e32 v227, 0xbfb8aa3b, v227
	v_exp_f32_e32 v190, v190
	v_exp_f32_e32 v237, v227
	v_rcp_f32_e32 v242, v189
	v_add_f32_e32 v189, 1.0, v239
	v_rcp_f32_e32 v239, v189
	v_pk_add_f32 v[236:237], v[236:237], 1.0 op_sel_hi:[1,0]
	v_pk_add_f32 v[190:191], v[190:191], 1.0 op_sel_hi:[1,0]
	v_add_f32_e32 v189, v157, v244
	v_pk_mul_f32 v[190:191], v[192:193], v[190:191]
	v_pk_mul_f32 v[192:193], v[238:239], v[236:237]
	v_med3_f32 v189, v189, s85, v226
	v_pk_mul_f32 v[100:101], v[100:101], v[192:193]
	v_add_f32_e32 v192, v153, v241
	v_med3_f32 v192, v192, s85, v226
	v_mul_f32_e32 v192, 0xbfb8aa3b, v192
	v_exp_f32_e32 v192, v192
	v_mul_f32_e32 v189, 0xbfb8aa3b, v189
	v_exp_f32_e32 v241, v189
	v_pk_mul_f32 v[98:99], v[98:99], v[190:191]
	v_add_f32_e32 v189, 1.0, v192
	v_rcp_f32_e32 v243, v189
	v_lshlrev_b32_e32 v189, 16, v194
	v_add_f32_e32 v189, v142, v189
	v_pk_add_f32 v[192:193], v[228:229], 1.0 op_sel_hi:[1,0]
	v_med3_f32 v189, v189, s85, v226
	v_pk_mul_f32 v[192:193], v[230:231], v[192:193]
	v_mul_f32_e32 v189, 0xbfb8aa3b, v189
	v_pk_mul_f32 v[94:95], v[94:95], v[192:193]
	v_lshlrev_b32_e32 v193, 16, v196
	v_exp_f32_e32 v189, v189
	v_add_f32_e32 v193, v134, v193
	v_pk_add_f32 v[190:191], v[240:241], 1.0 op_sel_hi:[1,0]
	v_med3_f32 v193, v193, s85, v226
	v_pk_mul_f32 v[190:191], v[242:243], v[190:191]
	v_mul_f32_e32 v193, 0xbfb8aa3b, v193
	v_pk_mul_f32 v[96:97], v[96:97], v[190:191]
	v_and_b32_e32 v191, 0xffff0000, v194
	s_waitcnt lgkmcnt(0)
; #define UNPK0(q_) ((f32x4){bf_lo((q_).x), bf_hi((q_).x), bf_lo((q_).y), bf_hi((q_).y)})
; #define UNPK1(q_) ((f32x4){bf_lo((q_).z), bf_hi((q_).z), bf_lo((q_).w), bf_hi((q_).w)})
;     static __device__ __forceinline__ float eneg(float g) { return __builtin_amdgcn_exp2f(-1.4426950408889634f * fminf(fmaxf(g, -30.f), 30.f)); }
;     __device__ __forceinline__ void mid(f32x4 (&acc)[2][2][4][2], const Unit& u, int wr, int wc, int fr, int fq) const {
;     ...
;             for (int m = 2 * (am & 1); m < 2 * (am & 1) + 2; ++m) {
;                 pa.stage(ra[m][0], ra[m][1]); const u32x4 ga0 = pa.get(0), ga1 = pa.get(1);
;                 asm volatile("" ::: "memory");
;                 pb.stage(rb[m][0], rb[m][1]); const u32x4 gb0 = pb.get(0), gb1 = pb.get(1);
;                 asm volatile("" ::: "memory");
; #pragma unroll
;                 for (int bj = 0; bj < 2; ++bj) { const u32x4 ga = bj ? ga1 : ga0, gb = bj ? gb1 : gb0;
;                     const f32x4 a0 = UNPK0(ga) + ba[bj][0], a1 = UNPK1(ga) + ba[bj][1], b0 = UNPK0(gb) + bb[bj][0], b1 = UNPK1(gb) + bb[bj][1];
; #pragma unroll
;                     for (int k = 0; k < 4; ++k) { acc[ai][bj][m][0][k] *= (1.0f + eneg(b0[k])) * __builtin_amdgcn_rcpf(1.0f + eneg(a0[k]));
;                                                   acc[ai][bj][m][1][k] *= (1.0f + eneg(b1[k])) * __builtin_amdgcn_rcpf(1.0f + eneg(a1[k])); } } }
	v_lshlrev_b32_e32 v194, 16, v234
	v_add_f32_e32 v189, 1.0, v189
	v_exp_f32_e32 v193, v193
	v_rcp_f32_e32 v192, v189
	v_add_f32_e32 v189, v138, v194
	v_add_f32_e32 v191, v143, v191
	v_med3_f32 v189, v189, s85, v226
	v_med3_f32 v191, v191, s85, v226
	v_mul_f32_e32 v189, 0xbfb8aa3b, v189
	v_mul_f32_e32 v191, 0xbfb8aa3b, v191
	v_lshlrev_b32_e32 v227, 16, v195
	v_and_b32_e32 v229, 0xffff0000, v195
	v_and_b32_e32 v195, 0xffff0000, v196
	v_lshlrev_b32_e32 v231, 16, v197
	v_and_b32_e32 v236, 0xffff0000, v197
	v_and_b32_e32 v197, 0xffff0000, v232
	v_exp_f32_e32 v194, v189
	v_add_f32_e32 v189, 1.0, v193
	v_exp_f32_e32 v193, v191
	v_rcp_f32_e32 v196, v189
	v_add_f32_e32 v189, v147, v197
	v_add_f32_e32 v195, v135, v195
	v_med3_f32 v189, v189, s85, v226
	v_med3_f32 v195, v195, s85, v226
	v_mul_f32_e32 v189, 0xbfb8aa3b, v189
	v_mul_f32_e32 v195, 0xbfb8aa3b, v195
	v_and_b32_e32 v230, 0xffff0000, v234
	v_exp_f32_e32 v191, v189
	v_add_f32_e32 v189, 1.0, v193
	v_exp_f32_e32 v197, v195
	v_rcp_f32_e32 v193, v189
	v_add_f32_e32 v189, v139, v230
	v_add_f32_e32 v227, v144, v227
	v_med3_f32 v189, v189, s85, v226
	v_med3_f32 v227, v227, s85, v226
	v_mul_f32_e32 v189, 0xbfb8aa3b, v189
	v_mul_f32_e32 v227, 0xbfb8aa3b, v227
	v_lshlrev_b32_e32 v228, 16, v233
	v_exp_f32_e32 v195, v189
	v_add_f32_e32 v189, 1.0, v197
	v_exp_f32_e32 v227, v227
	v_rcp_f32_e32 v197, v189
	v_add_f32_e32 v189, v148, v228
	v_med3_f32 v189, v189, s85, v226
	v_mul_f32_e32 v189, 0xbfb8aa3b, v189
	v_exp_f32_e32 v228, v189
	v_add_f32_e32 v189, 1.0, v227
	v_add_f32_e32 v227, v136, v231
	v_med3_f32 v227, v227, s85, v226
	v_mul_f32_e32 v227, 0xbfb8aa3b, v227
	v_lshlrev_b32_e32 v190, 16, v232
	v_lshlrev_b32_e32 v232, 16, v235
	v_exp_f32_e32 v227, v227
	v_add_f32_e32 v229, v145, v229
	v_rcp_f32_e32 v230, v189
	v_add_f32_e32 v189, v140, v232
	v_med3_f32 v229, v229, s85, v226
	v_med3_f32 v189, v189, s85, v226
	v_mul_f32_e32 v229, 0xbfb8aa3b, v229
	v_and_b32_e32 v233, 0xffff0000, v233
	v_mul_f32_e32 v189, 0xbfb8aa3b, v189
	v_exp_f32_e32 v231, v229
	v_add_f32_e32 v190, v146, v190
	v_exp_f32_e32 v232, v189
	v_add_f32_e32 v189, 1.0, v227
	v_add_f32_e32 v227, v149, v233
	v_med3_f32 v190, v190, s85, v226
	v_med3_f32 v227, v227, s85, v226
	v_mul_f32_e32 v190, 0xbfb8aa3b, v190
	v_mul_f32_e32 v227, 0xbfb8aa3b, v227
	v_exp_f32_e32 v190, v190
	v_exp_f32_e32 v229, v227
	v_rcp_f32_e32 v234, v189
	v_add_f32_e32 v189, 1.0, v231
	v_rcp_f32_e32 v231, v189
	v_pk_add_f32 v[228:229], v[228:229], 1.0 op_sel_hi:[1,0]
	v_pk_add_f32 v[190:191], v[190:191], 1.0 op_sel_hi:[1,0]
	v_and_b32_e32 v235, 0xffff0000, v235
	v_pk_mul_f32 v[190:191], v[192:193], v[190:191]
	v_pk_mul_f32 v[192:193], v[230:231], v[228:229]
	v_add_f32_e32 v189, v141, v235
	v_pk_mul_f32 v[92:93], v[92:93], v[192:193]
	v_add_f32_e32 v192, v137, v236
	v_med3_f32 v192, v192, s85, v226
	v_mul_f32_e32 v192, 0xbfb8aa3b, v192
	v_exp_f32_e32 v192, v192
	v_med3_f32 v189, v189, s85, v226
	v_mul_f32_e32 v189, 0xbfb8aa3b, v189
	v_exp_f32_e32 v233, v189
	v_add_f32_e32 v189, 1.0, v192
	v_rcp_f32_e32 v235, v189
	s_waitcnt vmcnt(3)
	ds_write_b128 v3, v[174:177]
	s_waitcnt vmcnt(2)
	ds_write_b128 v3, v[178:181] offset:1152
	ds_read_b128 v[174:177], v188
	ds_read_b128 v[178:181], v188 offset:64
	s_waitcnt vmcnt(1)
	ds_write_b128 v3, v[166:169]
	s_waitcnt vmcnt(0)
	ds_write_b128 v3, v[170:173] offset:1152
	ds_read_b128 v[166:169], v188
	ds_read_b128 v[170:173], v188 offset:64
	v_pk_mul_f32 v[90:91], v[90:91], v[190:191]
	v_pk_add_f32 v[190:191], v[232:233], 1.0 op_sel_hi:[1,0]
	s_waitcnt lgkmcnt(5)
	v_lshlrev_b32_e32 v189, 16, v174
	v_pk_mul_f32 v[190:191], v[234:235], v[190:191]
	s_waitcnt lgkmcnt(1)
	v_lshlrev_b32_e32 v227, 16, v169
	v_pk_mul_f32 v[88:89], v[88:89], v[190:191]
	v_and_b32_e32 v190, 0xffff0000, v174
	v_lshlrev_b32_e32 v174, 16, v176
	v_and_b32_e32 v228, 0xffff0000, v169
	v_add_f32_e32 v169, v150, v174
	v_pk_add_f32 v[192:193], v[194:195], 1.0 op_sel_hi:[1,0]
	v_med3_f32 v169, v169, s85, v226
	v_pk_mul_f32 v[192:193], v[196:197], v[192:193]
	v_mul_f32_e32 v169, 0xbfb8aa3b, v169
	v_pk_mul_f32 v[86:87], v[86:87], v[192:193]
	v_lshlrev_b32_e32 v191, 16, v175
	v_and_b32_e32 v193, 0xffff0000, v175
	v_and_b32_e32 v175, 0xffff0000, v176
	v_lshlrev_b32_e32 v192, 16, v167
	v_and_b32_e32 v196, 0xffff0000, v167
	v_lshlrev_b32_e32 v167, 16, v168
	v_exp_f32_e32 v169, v169
	v_add_f32_e32 v167, v154, v167
	v_add_f32_e32 v175, v151, v175
	v_med3_f32 v167, v167, s85, v226
	v_med3_f32 v175, v175, s85, v226
	v_mul_f32_e32 v167, 0xbfb8aa3b, v167
	v_mul_f32_e32 v175, 0xbfb8aa3b, v175
	v_and_b32_e32 v197, 0xffff0000, v168
	v_add_f32_e32 v168, v158, v189
	v_exp_f32_e32 v174, v167
	v_add_f32_e32 v167, 1.0, v169
	v_add_f32_e32 v169, v159, v190
	v_exp_f32_e32 v189, v175
	v_add_f32_e32 v190, v160, v191
	v_med3_f32 v190, v190, s85, v226
	v_lshlrev_b32_e32 v194, 16, v177
	v_and_b32_e32 v195, 0xffff0000, v177
	v_lshlrev_b32_e32 v176, 16, v166
	v_and_b32_e32 v177, 0xffff0000, v166
	v_mul_f32_e32 v190, 0xbfb8aa3b, v190
	v_add_f32_e32 v166, v162, v176
	v_rcp_f32_e32 v176, v167
	v_add_f32_e32 v167, v163, v177
	v_add_f32_e32 v177, v155, v197
	v_exp_f32_e32 v191, v190
	v_med3_f32 v175, v177, s85, v226
	v_add_f32_e32 v177, 1.0, v189
	v_add_f32_e32 v189, v164, v192
	v_med3_f32 v189, v189, s85, v226
	v_mul_f32_e32 v189, 0xbfb8aa3b, v189
	v_exp_f32_e32 v190, v189
	v_add_f32_e32 v189, 1.0, v191
	v_add_f32_e32 v191, v152, v194
	v_med3_f32 v191, v191, s85, v226
	v_mul_f32_e32 v191, 0xbfb8aa3b, v191
	v_exp_f32_e32 v191, v191
	v_add_f32_e32 v193, v161, v193
	v_med3_f32 v168, v168, s85, v226
	v_med3_f32 v169, v169, s85, v226
	v_rcp_f32_e32 v192, v189
	v_add_f32_e32 v189, v156, v227
	v_med3_f32 v193, v193, s85, v226
; #define UNPK0(q_) ((f32x4){bf_lo((q_).x), bf_hi((q_).x), bf_lo((q_).y), bf_hi((q_).y)})
; #define UNPK1(q_) ((f32x4){bf_lo((q_).z), bf_hi((q_).z), bf_lo((q_).w), bf_hi((q_).w)})
;     static __device__ __forceinline__ float eneg(float g) { return __builtin_amdgcn_exp2f(-1.4426950408889634f * fminf(fmaxf(g, -30.f), 30.f)); }
;     __device__ __forceinline__ void mid(f32x4 (&acc)[2][2][4][2], const Unit& u, int wr, int wc, int fr, int fq) const {
;     ...
;         for (int am = 0; am < 4; ++am) { const int ai = am >> 1;
;             u32x4 ra[4][2], rb[4][2];
; #pragma unroll
;             for (int m = 2 * (am & 1); m < 2 * (am & 1) + 2; ++m) { pa.fetch(ai, m, ra[m][0], ra[m][1]); pb.fetch(ai, m, rb[m][0], rb[m][1]); }
;             asm volatile("" ::: "memory");
; #pragma unroll
;             for (int m = 2 * (am & 1); m < 2 * (am & 1) + 2; ++m) {
;                 pa.stage(ra[m][0], ra[m][1]); const u32x4 ga0 = pa.get(0), ga1 = pa.get(1);
;                 asm volatile("" ::: "memory");
;                 pb.stage(rb[m][0], rb[m][1]); const u32x4 gb0 = pb.get(0), gb1 = pb.get(1);
;                 asm volatile("" ::: "memory");
; #pragma unroll
;                 for (int bj = 0; bj < 2; ++bj) { const u32x4 ga = bj ? ga1 : ga0, gb = bj ? gb1 : gb0;
;                     const f32x4 a0 = UNPK0(ga) + ba[bj][0], a1 = UNPK1(ga) + ba[bj][1], b0 = UNPK0(gb) + bb[bj][0], b1 = UNPK1(gb) + bb[bj][1];
; #pragma unroll
;                     for (int k = 0; k < 4; ++k) { acc[ai][bj][m][0][k] *= (1.0f + eneg(b0[k])) * __builtin_amdgcn_rcpf(1.0f + eneg(a0[k]));
;                                                   acc[ai][bj][m][1][k] *= (1.0f + eneg(b1[k])) * __builtin_amdgcn_rcpf(1.0f + eneg(a1[k])); } } }
	v_mul_f32_e32 v168, 0xbfb8aa3b, v168
	v_mul_f32_e32 v169, 0xbfb8aa3b, v169
	v_med3_f32 v189, v189, s85, v226
	v_mul_f32_e32 v193, 0xbfb8aa3b, v193
	v_exp_f32_e32 v168, v168
	v_exp_f32_e32 v169, v169
	v_mul_f32_e32 v189, 0xbfb8aa3b, v189
	v_exp_f32_e32 v193, v193
	v_exp_f32_e32 v194, v189
	v_add_f32_e32 v189, 1.0, v191
	v_add_f32_e32 v191, v165, v196
	v_med3_f32 v166, v166, s85, v226
	v_med3_f32 v167, v167, s85, v226
	v_med3_f32 v191, v191, s85, v226
	v_mul_f32_e32 v166, 0xbfb8aa3b, v166
	v_mul_f32_e32 v167, 0xbfb8aa3b, v167
	v_mul_f32_e32 v191, 0xbfb8aa3b, v191
	v_exp_f32_e32 v166, v166
	v_add_f32_e32 v168, 1.0, v168
	v_exp_f32_e32 v167, v167
	v_add_f32_e32 v169, 1.0, v169
	v_exp_f32_e32 v191, v191
	v_rcp_f32_e32 v196, v189
	v_add_f32_e32 v189, 1.0, v193
	v_rcp_f32_e32 v168, v168
	v_rcp_f32_e32 v169, v169
	v_rcp_f32_e32 v193, v189
	v_pk_add_f32 v[190:191], v[190:191], 1.0 op_sel_hi:[1,0]
	v_pk_add_f32 v[166:167], v[166:167], 1.0 op_sel_hi:[1,0]
	v_mul_f32_e32 v175, 0xbfb8aa3b, v175
	v_pk_mul_f32 v[166:167], v[168:169], v[166:167]
	v_pk_mul_f32 v[168:169], v[192:193], v[190:191]
	v_exp_f32_e32 v175, v175
	v_pk_mul_f32 v[84:85], v[84:85], v[168:169]
	v_add_f32_e32 v169, v153, v195
	v_med3_f32 v169, v169, s85, v226
	v_mul_f32_e32 v169, 0xbfb8aa3b, v169
	v_exp_f32_e32 v169, v169
	v_add_f32_e32 v168, v157, v228
	v_med3_f32 v168, v168, s85, v226
	v_mul_f32_e32 v168, 0xbfb8aa3b, v168
	v_rcp_f32_e32 v177, v177
	v_exp_f32_e32 v195, v168
	v_pk_mul_f32 v[82:83], v[82:83], v[166:167]
	v_add_f32_e32 v166, 1.0, v169
	v_rcp_f32_e32 v197, v166
	v_pk_add_f32 v[168:169], v[174:175], 1.0 op_sel_hi:[1,0]
	v_pk_add_f32 v[166:167], v[194:195], 1.0 op_sel_hi:[1,0]
	v_pk_mul_f32 v[168:169], v[176:177], v[168:169]
	v_pk_mul_f32 v[166:167], v[196:197], v[166:167]
	v_pk_mul_f32 v[78:79], v[78:79], v[168:169]
	v_lshlrev_b32_e32 v169, 16, v180
	v_pk_mul_f32 v[80:81], v[80:81], v[166:167]
	v_lshlrev_b32_e32 v166, 16, v178
	v_add_f32_e32 v169, v134, v169
	v_add_f32_e32 v166, v142, v166
	v_med3_f32 v169, v169, s85, v226
	v_med3_f32 v166, v166, s85, v226
	v_mul_f32_e32 v169, 0xbfb8aa3b, v169
	v_mul_f32_e32 v166, 0xbfb8aa3b, v166
	v_exp_f32_e32 v169, v169
	v_and_b32_e32 v167, 0xffff0000, v178
	v_and_b32_e32 v176, 0xffff0000, v180
	s_waitcnt lgkmcnt(0)
	v_lshlrev_b32_e32 v168, 16, v170
	v_and_b32_e32 v178, 0xffff0000, v170
	v_lshlrev_b32_e32 v180, 16, v171
	v_and_b32_e32 v189, 0xffff0000, v171
	v_lshlrev_b32_e32 v170, 16, v172
	v_and_b32_e32 v171, 0xffff0000, v172
	v_exp_f32_e32 v172, v166
	v_add_f32_e32 v168, v146, v168
	v_add_f32_e32 v169, 1.0, v169
	v_med3_f32 v166, v168, s85, v226
	v_add_f32_e32 v168, 1.0, v172
	v_rcp_f32_e32 v172, v169
	v_add_f32_e32 v169, v147, v178
	v_add_co_u32_e32 v178, vcc, s79, v186
	v_lshlrev_b32_e32 v174, 16, v179
	v_and_b32_e32 v175, 0xffff0000, v179
	v_addc_co_u32_e32 v179, vcc, 0, v187, vcc
	v_add_co_u32_e32 v186, vcc, s86, v186
	v_add_f32_e32 v167, v143, v167
	s_nop 0
	v_addc_co_u32_e32 v187, vcc, 0, v187, vcc
	global_load_dwordx4 v[190:193], v[186:187], off offset:-4096
	global_load_dwordx4 v[194:197], v[178:179], off offset:1024
	v_add_co_u32_e32 v236, vcc, s79, v4
	v_med3_f32 v167, v167, s85, v226
	s_nop 0
	v_addc_co_u32_e32 v237, vcc, 0, v5, vcc
	v_add_co_u32_e32 v4, vcc, s86, v4
	v_mul_f32_e32 v167, 0xbfb8aa3b, v167
	s_nop 0
	v_addc_co_u32_e32 v5, vcc, 0, v5, vcc
	global_load_dwordx4 v[228:231], v[4:5], off offset:-4096
	global_load_dwordx4 v[232:235], v[236:237], off offset:1024
	v_lshlrev_b32_e32 v227, 16, v173
	v_and_b32_e32 v239, 0xffff0000, v173
	v_exp_f32_e32 v173, v167
	v_add_f32_e32 v174, v144, v174
	v_med3_f32 v174, v174, s85, v226
	v_lshlrev_b32_e32 v177, 16, v181
	v_mul_f32_e32 v174, 0xbfb8aa3b, v174
	v_med3_f32 v167, v169, s85, v226
	v_add_f32_e32 v169, 1.0, v173
	v_add_f32_e32 v173, v135, v176
	v_add_f32_e32 v176, v148, v180
	v_exp_f32_e32 v180, v174
	v_add_f32_e32 v177, v136, v177
	v_med3_f32 v177, v177, s85, v226
	v_add_f32_e32 v175, v145, v175
	v_mul_f32_e32 v177, 0xbfb8aa3b, v177
	v_med3_f32 v175, v175, s85, v226
	v_exp_f32_e32 v177, v177
	v_mul_f32_e32 v175, 0xbfb8aa3b, v175
	v_med3_f32 v174, v176, s85, v226
	v_add_f32_e32 v176, 1.0, v180
	v_add_f32_e32 v180, v140, v227
	v_exp_f32_e32 v227, v175
	v_add_f32_e32 v189, v149, v189
	v_med3_f32 v189, v189, s85, v226
	v_mul_f32_e32 v166, 0xbfb8aa3b, v166
	v_mul_f32_e32 v167, 0xbfb8aa3b, v167
	v_mul_f32_e32 v174, 0xbfb8aa3b, v174
	v_add_f32_e32 v177, 1.0, v177
	v_mul_f32_e32 v175, 0xbfb8aa3b, v189
	v_exp_f32_e32 v166, v166
	v_exp_f32_e32 v167, v167
	v_exp_f32_e32 v174, v174
	v_exp_f32_e32 v175, v175
	v_rcp_f32_e32 v238, v177
	v_add_f32_e32 v177, 1.0, v227
	v_rcp_f32_e32 v168, v168
	v_rcp_f32_e32 v169, v169
	v_rcp_f32_e32 v176, v176
	v_rcp_f32_e32 v177, v177
	v_pk_add_f32 v[174:175], v[174:175], 1.0 op_sel_hi:[1,0]
	v_pk_add_f32 v[166:167], v[166:167], 1.0 op_sel_hi:[1,0]
	v_and_b32_e32 v181, 0xffff0000, v181
	v_pk_mul_f32 v[166:167], v[168:169], v[166:167]
	v_pk_mul_f32 v[168:169], v[176:177], v[174:175]
	v_med3_f32 v173, v173, s85, v226
	v_pk_mul_f32 v[76:77], v[76:77], v[168:169]
	v_add_f32_e32 v169, v137, v181
	v_med3_f32 v169, v169, s85, v226
	v_mul_f32_e32 v173, 0xbfb8aa3b, v173
	v_mul_f32_e32 v169, 0xbfb8aa3b, v169
	v_exp_f32_e32 v173, v173
	v_exp_f32_e32 v169, v169
	v_add_f32_e32 v170, v138, v170
	v_add_f32_e32 v171, v139, v171
	v_add_f32_e32 v168, v141, v239
	v_med3_f32 v170, v170, s85, v226
	v_med3_f32 v171, v171, s85, v226
	v_med3_f32 v180, v180, s85, v226
	v_med3_f32 v168, v168, s85, v226
	v_mul_f32_e32 v170, 0xbfb8aa3b, v170
	v_mul_f32_e32 v171, 0xbfb8aa3b, v171
	v_mul_f32_e32 v180, 0xbfb8aa3b, v180
	v_mul_f32_e32 v168, 0xbfb8aa3b, v168
	v_exp_f32_e32 v170, v170
	v_exp_f32_e32 v171, v171
	v_add_f32_e32 v173, 1.0, v173
	v_exp_f32_e32 v180, v180
	v_exp_f32_e32 v181, v168
	v_pk_mul_f32 v[74:75], v[74:75], v[166:167]
	v_add_f32_e32 v166, 1.0, v169
	v_rcp_f32_e32 v173, v173
	v_rcp_f32_e32 v239, v166
	v_pk_add_f32 v[166:167], v[180:181], 1.0 op_sel_hi:[1,0]
	v_pk_add_f32 v[168:169], v[170:171], 1.0 op_sel_hi:[1,0]
	v_pk_mul_f32 v[166:167], v[238:239], v[166:167]
	v_pk_mul_f32 v[168:169], v[172:173], v[168:169]
	v_pk_mul_f32 v[72:73], v[72:73], v[166:167]
	v_pk_mul_f32 v[70:71], v[70:71], v[168:169]
	global_load_dwordx4 v[174:177], v[178:179], off offset:2048
	s_nop 0
	global_load_dwordx4 v[178:181], v[178:179], off offset:3072
	s_nop 0
	global_load_dwordx4 v[166:169], v[236:237], off offset:2048
	global_load_dwordx4 v[170:173], v[236:237], off offset:3072
	s_waitcnt vmcnt(7)
; #define UNPK0(q_) ((f32x4){bf_lo((q_).x), bf_hi((q_).x), bf_lo((q_).y), bf_hi((q_).y)})
; #define UNPK1(q_) ((f32x4){bf_lo((q_).z), bf_hi((q_).z), bf_lo((q_).w), bf_hi((q_).w)})
;     static __device__ __forceinline__ float eneg(float g) { return __builtin_amdgcn_exp2f(-1.4426950408889634f * fminf(fmaxf(g, -30.f), 30.f)); }
;     __device__ __forceinline__ void mid(f32x4 (&acc)[2][2][4][2], const Unit& u, int wr, int wc, int fr, int fq) const {
;     ...
;             for (int m = 2 * (am & 1); m < 2 * (am & 1) + 2; ++m) {
;                 pa.stage(ra[m][0], ra[m][1]); const u32x4 ga0 = pa.get(0), ga1 = pa.get(1);
;                 asm volatile("" ::: "memory");
;                 pb.stage(rb[m][0], rb[m][1]); const u32x4 gb0 = pb.get(0), gb1 = pb.get(1);
;                 asm volatile("" ::: "memory");
; #pragma unroll
;                 for (int bj = 0; bj < 2; ++bj) { const u32x4 ga = bj ? ga1 : ga0, gb = bj ? gb1 : gb0;
;                     const f32x4 a0 = UNPK0(ga) + ba[bj][0], a1 = UNPK1(ga) + ba[bj][1], b0 = UNPK0(gb) + bb[bj][0], b1 = UNPK1(gb) + bb[bj][1];
; #pragma unroll
;                     for (int k = 0; k < 4; ++k) { acc[ai][bj][m][0][k] *= (1.0f + eneg(b0[k])) * __builtin_amdgcn_rcpf(1.0f + eneg(a0[k]));
;                                                   acc[ai][bj][m][1][k] *= (1.0f + eneg(b1[k])) * __builtin_amdgcn_rcpf(1.0f + eneg(a1[k])); } } }
	ds_write_b128 v3, v[190:193]
	s_waitcnt vmcnt(6)
	ds_write_b128 v3, v[194:197] offset:1152
	ds_read_b128 v[190:193], v188
	ds_read_b128 v[194:197], v188 offset:64
	s_waitcnt vmcnt(5)
	ds_write_b128 v3, v[228:231]
	s_waitcnt vmcnt(4)
	ds_write_b128 v3, v[232:235] offset:1152
	ds_read_b128 v[228:231], v188
	ds_read_b128 v[232:235], v188 offset:64
	s_waitcnt lgkmcnt(5)
	v_lshlrev_b32_e32 v189, 16, v190
	v_add_f32_e32 v189, v158, v189
	v_med3_f32 v189, v189, s85, v226
	v_mul_f32_e32 v189, 0xbfb8aa3b, v189
	v_lshlrev_b32_e32 v236, 16, v191
	v_and_b32_e32 v237, 0xffff0000, v191
	v_lshlrev_b32_e32 v191, 16, v192
	v_exp_f32_e32 v189, v189
	v_add_f32_e32 v191, v150, v191
	v_med3_f32 v191, v191, s85, v226
	v_mul_f32_e32 v191, 0xbfb8aa3b, v191
	v_and_b32_e32 v227, 0xffff0000, v190
	v_lshlrev_b32_e32 v239, 16, v193
	v_and_b32_e32 v241, 0xffff0000, v193
	s_waitcnt lgkmcnt(1)
	v_lshlrev_b32_e32 v190, 16, v228
	v_and_b32_e32 v193, 0xffff0000, v228
	v_lshlrev_b32_e32 v228, 16, v230
	v_add_f32_e32 v189, 1.0, v189
	v_exp_f32_e32 v191, v191
	v_and_b32_e32 v238, 0xffff0000, v192
	v_rcp_f32_e32 v192, v189
	v_add_f32_e32 v189, v154, v228
	v_med3_f32 v189, v189, s85, v226
	v_mul_f32_e32 v189, 0xbfb8aa3b, v189
	v_exp_f32_e32 v228, v189
	v_add_f32_e32 v189, 1.0, v191
	v_add_f32_e32 v191, v159, v227
	v_med3_f32 v191, v191, s85, v226
	v_mul_f32_e32 v191, 0xbfb8aa3b, v191
	v_lshlrev_b32_e32 v240, 16, v229
	v_and_b32_e32 v242, 0xffff0000, v229
	v_and_b32_e32 v229, 0xffff0000, v230
	v_rcp_f32_e32 v230, v189
	v_add_f32_e32 v189, v163, v193
	v_exp_f32_e32 v193, v191
	v_add_f32_e32 v227, v151, v238
	v_med3_f32 v189, v189, s85, v226
	v_med3_f32 v227, v227, s85, v226
	v_mul_f32_e32 v189, 0xbfb8aa3b, v189
	v_mul_f32_e32 v227, 0xbfb8aa3b, v227
	v_exp_f32_e32 v191, v189
	v_add_f32_e32 v189, 1.0, v193
	v_exp_f32_e32 v227, v227
	v_rcp_f32_e32 v193, v189
	v_add_f32_e32 v189, v155, v229
	v_med3_f32 v189, v189, s85, v226
	v_mul_f32_e32 v189, 0xbfb8aa3b, v189
	v_exp_f32_e32 v229, v189
	v_add_f32_e32 v189, 1.0, v227
	v_add_f32_e32 v227, v160, v236
	v_med3_f32 v227, v227, s85, v226
	v_mul_f32_e32 v227, 0xbfb8aa3b, v227
	v_exp_f32_e32 v227, v227
	v_lshlrev_b32_e32 v243, 16, v231
	v_and_b32_e32 v244, 0xffff0000, v231
	v_rcp_f32_e32 v231, v189
	v_add_f32_e32 v189, v164, v240
	v_med3_f32 v189, v189, s85, v226
	v_mul_f32_e32 v189, 0xbfb8aa3b, v189
	v_exp_f32_e32 v236, v189
	v_add_f32_e32 v189, 1.0, v227
	v_add_f32_e32 v227, v152, v239
	v_med3_f32 v227, v227, s85, v226
	v_mul_f32_e32 v227, 0xbfb8aa3b, v227
	v_exp_f32_e32 v227, v227
	v_add_f32_e32 v237, v161, v237
	v_rcp_f32_e32 v238, v189
	v_add_f32_e32 v189, v156, v243
	v_med3_f32 v237, v237, s85, v226
	v_med3_f32 v189, v189, s85, v226
	v_mul_f32_e32 v237, 0xbfb8aa3b, v237
	v_mul_f32_e32 v189, 0xbfb8aa3b, v189
	v_exp_f32_e32 v239, v237
	v_add_f32_e32 v190, v162, v190
	v_exp_f32_e32 v240, v189
	v_add_f32_e32 v189, 1.0, v227
	v_add_f32_e32 v227, v165, v242
	v_med3_f32 v190, v190, s85, v226
	v_med3_f32 v227, v227, s85, v226
	v_mul_f32_e32 v190, 0xbfb8aa3b, v190
	v_mul_f32_e32 v227, 0xbfb8aa3b, v227
	v_exp_f32_e32 v190, v190
	v_exp_f32_e32 v237, v227
	v_rcp_f32_e32 v242, v189
	v_add_f32_e32 v189, 1.0, v239
	v_rcp_f32_e32 v239, v189
	v_pk_add_f32 v[236:237], v[236:237], 1.0 op_sel_hi:[1,0]
	v_pk_add_f32 v[190:191], v[190:191], 1.0 op_sel_hi:[1,0]
	v_add_f32_e32 v189, v157, v244
	v_pk_mul_f32 v[190:191], v[192:193], v[190:191]
	v_pk_mul_f32 v[192:193], v[238:239], v[236:237]
	v_med3_f32 v189, v189, s85, v226
	v_pk_mul_f32 v[68:69], v[68:69], v[192:193]
	v_add_f32_e32 v192, v153, v241
	v_med3_f32 v192, v192, s85, v226
	v_mul_f32_e32 v192, 0xbfb8aa3b, v192
	v_exp_f32_e32 v192, v192
	v_mul_f32_e32 v189, 0xbfb8aa3b, v189
	v_exp_f32_e32 v241, v189
	v_pk_mul_f32 v[66:67], v[66:67], v[190:191]
	v_add_f32_e32 v189, 1.0, v192
	v_rcp_f32_e32 v243, v189
	v_lshlrev_b32_e32 v189, 16, v194
	v_add_f32_e32 v189, v142, v189
	v_pk_add_f32 v[192:193], v[228:229], 1.0 op_sel_hi:[1,0]
	v_med3_f32 v189, v189, s85, v226
	v_pk_mul_f32 v[192:193], v[230:231], v[192:193]
	v_mul_f32_e32 v189, 0xbfb8aa3b, v189
	v_pk_mul_f32 v[62:63], v[62:63], v[192:193]
	v_lshlrev_b32_e32 v193, 16, v196
	v_exp_f32_e32 v189, v189
	v_add_f32_e32 v193, v134, v193
	v_pk_add_f32 v[190:191], v[240:241], 1.0 op_sel_hi:[1,0]
	v_med3_f32 v193, v193, s85, v226
	v_pk_mul_f32 v[190:191], v[242:243], v[190:191]
	v_mul_f32_e32 v193, 0xbfb8aa3b, v193
	v_pk_mul_f32 v[64:65], v[64:65], v[190:191]
	v_and_b32_e32 v191, 0xffff0000, v194
	s_waitcnt lgkmcnt(0)
; #define UNPK0(q_) ((f32x4){bf_lo((q_).x), bf_hi((q_).x), bf_lo((q_).y), bf_hi((q_).y)})
; #define UNPK1(q_) ((f32x4){bf_lo((q_).z), bf_hi((q_).z), bf_lo((q_).w), bf_hi((q_).w)})
;     static __device__ __forceinline__ float eneg(float g) { return __builtin_amdgcn_exp2f(-1.4426950408889634f * fminf(fmaxf(g, -30.f), 30.f)); }
;     __device__ __forceinline__ void mid(f32x4 (&acc)[2][2][4][2], const Unit& u, int wr, int wc, int fr, int fq) const {
;     ...
;             for (int m = 2 * (am & 1); m < 2 * (am & 1) + 2; ++m) {
;                 pa.stage(ra[m][0], ra[m][1]); const u32x4 ga0 = pa.get(0), ga1 = pa.get(1);
;                 asm volatile("" ::: "memory");
;                 pb.stage(rb[m][0], rb[m][1]); const u32x4 gb0 = pb.get(0), gb1 = pb.get(1);
;                 asm volatile("" ::: "memory");
; #pragma unroll
;                 for (int bj = 0; bj < 2; ++bj) { const u32x4 ga = bj ? ga1 : ga0, gb = bj ? gb1 : gb0;
;                     const f32x4 a0 = UNPK0(ga) + ba[bj][0], a1 = UNPK1(ga) + ba[bj][1], b0 = UNPK0(gb) + bb[bj][0], b1 = UNPK1(gb) + bb[bj][1];
; #pragma unroll
;                     for (int k = 0; k < 4; ++k) { acc[ai][bj][m][0][k] *= (1.0f + eneg(b0[k])) * __builtin_amdgcn_rcpf(1.0f + eneg(a0[k]));
;                                                   acc[ai][bj][m][1][k] *= (1.0f + eneg(b1[k])) * __builtin_amdgcn_rcpf(1.0f + eneg(a1[k])); } } }
	v_lshlrev_b32_e32 v194, 16, v234
	v_add_f32_e32 v189, 1.0, v189
	v_exp_f32_e32 v193, v193
	v_rcp_f32_e32 v192, v189
	v_add_f32_e32 v189, v138, v194
	v_add_f32_e32 v191, v143, v191
	v_med3_f32 v189, v189, s85, v226
	v_med3_f32 v191, v191, s85, v226
	v_mul_f32_e32 v189, 0xbfb8aa3b, v189
	v_mul_f32_e32 v191, 0xbfb8aa3b, v191
	v_lshlrev_b32_e32 v227, 16, v195
	v_and_b32_e32 v229, 0xffff0000, v195
	v_and_b32_e32 v195, 0xffff0000, v196
	v_lshlrev_b32_e32 v231, 16, v197
	v_and_b32_e32 v236, 0xffff0000, v197
	v_and_b32_e32 v197, 0xffff0000, v232
	v_exp_f32_e32 v194, v189
	v_add_f32_e32 v189, 1.0, v193
	v_exp_f32_e32 v193, v191
	v_rcp_f32_e32 v196, v189
	v_add_f32_e32 v189, v147, v197
	v_add_f32_e32 v195, v135, v195
	v_med3_f32 v189, v189, s85, v226
	v_med3_f32 v195, v195, s85, v226
	v_mul_f32_e32 v189, 0xbfb8aa3b, v189
	v_mul_f32_e32 v195, 0xbfb8aa3b, v195
	v_and_b32_e32 v230, 0xffff0000, v234
	v_exp_f32_e32 v191, v189
	v_add_f32_e32 v189, 1.0, v193
	v_exp_f32_e32 v197, v195
	v_rcp_f32_e32 v193, v189
	v_add_f32_e32 v189, v139, v230
	v_add_f32_e32 v227, v144, v227
	v_med3_f32 v189, v189, s85, v226
	v_med3_f32 v227, v227, s85, v226
	v_mul_f32_e32 v189, 0xbfb8aa3b, v189
	v_mul_f32_e32 v227, 0xbfb8aa3b, v227
	v_lshlrev_b32_e32 v228, 16, v233
	v_exp_f32_e32 v195, v189
	v_add_f32_e32 v189, 1.0, v197
	v_exp_f32_e32 v227, v227
	v_rcp_f32_e32 v197, v189
	v_add_f32_e32 v189, v148, v228
	v_med3_f32 v189, v189, s85, v226
	v_mul_f32_e32 v189, 0xbfb8aa3b, v189
	v_exp_f32_e32 v228, v189
	v_add_f32_e32 v189, 1.0, v227
	v_add_f32_e32 v227, v136, v231
	v_med3_f32 v227, v227, s85, v226
	v_mul_f32_e32 v227, 0xbfb8aa3b, v227
	v_lshlrev_b32_e32 v190, 16, v232
	v_lshlrev_b32_e32 v232, 16, v235
	v_exp_f32_e32 v227, v227
	v_add_f32_e32 v229, v145, v229
	v_rcp_f32_e32 v230, v189
	v_add_f32_e32 v189, v140, v232
	v_med3_f32 v229, v229, s85, v226
	v_med3_f32 v189, v189, s85, v226
	v_mul_f32_e32 v229, 0xbfb8aa3b, v229
	v_and_b32_e32 v233, 0xffff0000, v233
	v_mul_f32_e32 v189, 0xbfb8aa3b, v189
	v_exp_f32_e32 v231, v229
	v_add_f32_e32 v190, v146, v190
	v_exp_f32_e32 v232, v189
	v_add_f32_e32 v189, 1.0, v227
	v_add_f32_e32 v227, v149, v233
	v_med3_f32 v190, v190, s85, v226
	v_med3_f32 v227, v227, s85, v226
	v_mul_f32_e32 v190, 0xbfb8aa3b, v190
	v_mul_f32_e32 v227, 0xbfb8aa3b, v227
	v_exp_f32_e32 v190, v190
	v_exp_f32_e32 v229, v227
	v_rcp_f32_e32 v234, v189
	v_add_f32_e32 v189, 1.0, v231
	v_rcp_f32_e32 v231, v189
	v_pk_add_f32 v[228:229], v[228:229], 1.0 op_sel_hi:[1,0]
	v_pk_add_f32 v[190:191], v[190:191], 1.0 op_sel_hi:[1,0]
	v_and_b32_e32 v235, 0xffff0000, v235
	v_pk_mul_f32 v[190:191], v[192:193], v[190:191]
	v_pk_mul_f32 v[192:193], v[230:231], v[228:229]
	v_add_f32_e32 v189, v141, v235
	v_pk_mul_f32 v[60:61], v[60:61], v[192:193]
	v_add_f32_e32 v192, v137, v236
	v_med3_f32 v192, v192, s85, v226
	v_mul_f32_e32 v192, 0xbfb8aa3b, v192
	v_exp_f32_e32 v192, v192
	v_med3_f32 v189, v189, s85, v226
	v_mul_f32_e32 v189, 0xbfb8aa3b, v189
	v_exp_f32_e32 v233, v189
	v_add_f32_e32 v189, 1.0, v192
	v_rcp_f32_e32 v235, v189
	s_waitcnt vmcnt(3)
	ds_write_b128 v3, v[174:177]
	s_waitcnt vmcnt(2)
	ds_write_b128 v3, v[178:181] offset:1152
	ds_read_b128 v[174:177], v188
	ds_read_b128 v[178:181], v188 offset:64
	s_waitcnt vmcnt(1)
	ds_write_b128 v3, v[166:169]
	s_waitcnt vmcnt(0)
	ds_write_b128 v3, v[170:173] offset:1152
	ds_read_b128 v[166:169], v188
	ds_read_b128 v[170:173], v188 offset:64
	v_pk_mul_f32 v[58:59], v[58:59], v[190:191]
	v_pk_add_f32 v[190:191], v[232:233], 1.0 op_sel_hi:[1,0]
	s_waitcnt lgkmcnt(5)
	v_lshlrev_b32_e32 v189, 16, v174
	v_pk_mul_f32 v[190:191], v[234:235], v[190:191]
	s_waitcnt lgkmcnt(1)
	v_lshlrev_b32_e32 v227, 16, v169
	v_pk_mul_f32 v[56:57], v[56:57], v[190:191]
	v_and_b32_e32 v190, 0xffff0000, v174
	v_lshlrev_b32_e32 v174, 16, v176
	v_and_b32_e32 v228, 0xffff0000, v169
	v_add_f32_e32 v169, v150, v174
	v_pk_add_f32 v[192:193], v[194:195], 1.0 op_sel_hi:[1,0]
	v_med3_f32 v169, v169, s85, v226
	v_pk_mul_f32 v[192:193], v[196:197], v[192:193]
	v_mul_f32_e32 v169, 0xbfb8aa3b, v169
	v_pk_mul_f32 v[54:55], v[54:55], v[192:193]
	v_lshlrev_b32_e32 v191, 16, v175
	v_and_b32_e32 v193, 0xffff0000, v175
	v_and_b32_e32 v175, 0xffff0000, v176
	v_lshlrev_b32_e32 v192, 16, v167
	v_and_b32_e32 v196, 0xffff0000, v167
	v_lshlrev_b32_e32 v167, 16, v168
	v_exp_f32_e32 v169, v169
	v_add_f32_e32 v167, v154, v167
	v_add_f32_e32 v175, v151, v175
	v_med3_f32 v167, v167, s85, v226
	v_med3_f32 v175, v175, s85, v226
	v_mul_f32_e32 v167, 0xbfb8aa3b, v167
	v_mul_f32_e32 v175, 0xbfb8aa3b, v175
	v_and_b32_e32 v197, 0xffff0000, v168
	v_add_f32_e32 v168, v158, v189
	v_exp_f32_e32 v174, v167
	v_add_f32_e32 v167, 1.0, v169
	v_add_f32_e32 v169, v159, v190
	v_exp_f32_e32 v189, v175
	v_add_f32_e32 v190, v160, v191
	v_med3_f32 v190, v190, s85, v226
	v_lshlrev_b32_e32 v194, 16, v177
	v_and_b32_e32 v195, 0xffff0000, v177
	v_lshlrev_b32_e32 v176, 16, v166
	v_and_b32_e32 v177, 0xffff0000, v166
	v_mul_f32_e32 v190, 0xbfb8aa3b, v190
	v_add_f32_e32 v166, v162, v176
	v_rcp_f32_e32 v176, v167
	v_add_f32_e32 v167, v163, v177
	v_add_f32_e32 v177, v155, v197
	v_exp_f32_e32 v191, v190
	v_med3_f32 v175, v177, s85, v226
	v_add_f32_e32 v177, 1.0, v189
	v_add_f32_e32 v189, v164, v192
	v_med3_f32 v189, v189, s85, v226
	v_mul_f32_e32 v189, 0xbfb8aa3b, v189
	v_exp_f32_e32 v190, v189
	v_add_f32_e32 v189, 1.0, v191
	v_add_f32_e32 v191, v152, v194
	v_med3_f32 v191, v191, s85, v226
	v_mul_f32_e32 v191, 0xbfb8aa3b, v191
	v_exp_f32_e32 v191, v191
	v_add_f32_e32 v193, v161, v193
	v_med3_f32 v168, v168, s85, v226
	v_med3_f32 v169, v169, s85, v226
	v_rcp_f32_e32 v192, v189
	v_add_f32_e32 v189, v156, v227
	v_med3_f32 v193, v193, s85, v226
; #define UNPK0(q_) ((f32x4){bf_lo((q_).x), bf_hi((q_).x), bf_lo((q_).y), bf_hi((q_).y)})
; #define UNPK1(q_) ((f32x4){bf_lo((q_).z), bf_hi((q_).z), bf_lo((q_).w), bf_hi((q_).w)})
;     static __device__ __forceinline__ float eneg(float g) { return __builtin_amdgcn_exp2f(-1.4426950408889634f * fminf(fmaxf(g, -30.f), 30.f)); }
;     __device__ __forceinline__ void mid(f32x4 (&acc)[2][2][4][2], const Unit& u, int wr, int wc, int fr, int fq) const {
;     ...
;         for (int am = 0; am < 4; ++am) { const int ai = am >> 1;
;             u32x4 ra[4][2], rb[4][2];
; #pragma unroll
;             for (int m = 2 * (am & 1); m < 2 * (am & 1) + 2; ++m) { pa.fetch(ai, m, ra[m][0], ra[m][1]); pb.fetch(ai, m, rb[m][0], rb[m][1]); }
;             asm volatile("" ::: "memory");
; #pragma unroll
;             for (int m = 2 * (am & 1); m < 2 * (am & 1) + 2; ++m) {
;                 pa.stage(ra[m][0], ra[m][1]); const u32x4 ga0 = pa.get(0), ga1 = pa.get(1);
;                 asm volatile("" ::: "memory");
;                 pb.stage(rb[m][0], rb[m][1]); const u32x4 gb0 = pb.get(0), gb1 = pb.get(1);
;                 asm volatile("" ::: "memory");
; #pragma unroll
;                 for (int bj = 0; bj < 2; ++bj) { const u32x4 ga = bj ? ga1 : ga0, gb = bj ? gb1 : gb0;
;                     const f32x4 a0 = UNPK0(ga) + ba[bj][0], a1 = UNPK1(ga) + ba[bj][1], b0 = UNPK0(gb) + bb[bj][0], b1 = UNPK1(gb) + bb[bj][1];
; #pragma unroll
;                     for (int k = 0; k < 4; ++k) { acc[ai][bj][m][0][k] *= (1.0f + eneg(b0[k])) * __builtin_amdgcn_rcpf(1.0f + eneg(a0[k]));
;                                                   acc[ai][bj][m][1][k] *= (1.0f + eneg(b1[k])) * __builtin_amdgcn_rcpf(1.0f + eneg(a1[k])); } } }
	v_mul_f32_e32 v168, 0xbfb8aa3b, v168
	v_mul_f32_e32 v169, 0xbfb8aa3b, v169
	v_med3_f32 v189, v189, s85, v226
	v_mul_f32_e32 v193, 0xbfb8aa3b, v193
	v_exp_f32_e32 v168, v168
	v_exp_f32_e32 v169, v169
	v_mul_f32_e32 v189, 0xbfb8aa3b, v189
	v_exp_f32_e32 v193, v193
	v_exp_f32_e32 v194, v189
	v_add_f32_e32 v189, 1.0, v191
	v_add_f32_e32 v191, v165, v196
	v_med3_f32 v166, v166, s85, v226
	v_med3_f32 v167, v167, s85, v226
	v_med3_f32 v191, v191, s85, v226
	v_mul_f32_e32 v166, 0xbfb8aa3b, v166
	v_mul_f32_e32 v167, 0xbfb8aa3b, v167
	v_mul_f32_e32 v191, 0xbfb8aa3b, v191
	v_exp_f32_e32 v166, v166
	v_add_f32_e32 v168, 1.0, v168
	v_exp_f32_e32 v167, v167
	v_add_f32_e32 v169, 1.0, v169
	v_exp_f32_e32 v191, v191
	v_rcp_f32_e32 v196, v189
	v_add_f32_e32 v189, 1.0, v193
	v_rcp_f32_e32 v168, v168
	v_rcp_f32_e32 v169, v169
	v_rcp_f32_e32 v193, v189
	v_pk_add_f32 v[190:191], v[190:191], 1.0 op_sel_hi:[1,0]
	v_pk_add_f32 v[166:167], v[166:167], 1.0 op_sel_hi:[1,0]
	v_mul_f32_e32 v175, 0xbfb8aa3b, v175
	v_pk_mul_f32 v[166:167], v[168:169], v[166:167]
	v_pk_mul_f32 v[168:169], v[192:193], v[190:191]
	v_pk_mul_f32 v[50:51], v[50:51], v[166:167]
	v_pk_mul_f32 v[52:53], v[52:53], v[168:169]
	v_add_f32_e32 v169, v153, v195
	v_med3_f32 v169, v169, s85, v226
	v_mul_f32_e32 v169, 0xbfb8aa3b, v169
	v_exp_f32_e32 v169, v169
	v_add_f32_e32 v168, v157, v228
	v_med3_f32 v168, v168, s85, v226
	v_mul_f32_e32 v168, 0xbfb8aa3b, v168
	v_exp_f32_e32 v195, v168
	v_add_f32_e32 v166, 1.0, v169
	v_rcp_f32_e32 v197, v166
	v_exp_f32_e32 v175, v175
	v_pk_add_f32 v[166:167], v[194:195], 1.0 op_sel_hi:[1,0]
	v_rcp_f32_e32 v177, v177
	v_pk_mul_f32 v[166:167], v[196:197], v[166:167]
	global_load_dwordx4 v[190:193], v[186:187], off
	global_load_dwordx4 v[194:197], v[186:187], off offset:1024
	global_load_dwordx4 v[228:231], v[4:5], off
	global_load_dwordx4 v[232:235], v[4:5], off offset:1024
	v_pk_add_f32 v[168:169], v[174:175], 1.0 op_sel_hi:[1,0]
	v_pk_mul_f32 v[48:49], v[48:49], v[166:167]
	v_pk_mul_f32 v[168:169], v[176:177], v[168:169]
	v_lshlrev_b32_e32 v166, 16, v178
	v_pk_mul_f32 v[46:47], v[46:47], v[168:169]
	v_lshlrev_b32_e32 v169, 16, v180
	v_add_f32_e32 v169, v134, v169
	v_and_b32_e32 v167, 0xffff0000, v178
	v_add_f32_e32 v166, v142, v166
	v_med3_f32 v169, v169, s85, v226
	v_med3_f32 v166, v166, s85, v226
	v_mul_f32_e32 v169, 0xbfb8aa3b, v169
	v_add_f32_e32 v167, v143, v167
	v_mul_f32_e32 v166, 0xbfb8aa3b, v166
	v_exp_f32_e32 v169, v169
	v_med3_f32 v167, v167, s85, v226
	v_lshlrev_b32_e32 v174, 16, v179
	v_and_b32_e32 v175, 0xffff0000, v179
	v_and_b32_e32 v176, 0xffff0000, v180
	v_lshlrev_b32_e32 v177, 16, v181
	v_and_b32_e32 v179, 0xffff0000, v181
	s_waitcnt lgkmcnt(0)
	v_lshlrev_b32_e32 v168, 16, v170
	v_and_b32_e32 v178, 0xffff0000, v170
	v_lshlrev_b32_e32 v180, 16, v171
	v_and_b32_e32 v181, 0xffff0000, v171
	v_lshlrev_b32_e32 v170, 16, v172
	v_and_b32_e32 v171, 0xffff0000, v172
	v_exp_f32_e32 v172, v166
	v_mul_f32_e32 v167, 0xbfb8aa3b, v167
	v_lshlrev_b32_e32 v189, 16, v173
	v_and_b32_e32 v227, 0xffff0000, v173
	v_exp_f32_e32 v173, v167
	v_add_f32_e32 v177, v136, v177
	v_add_f32_e32 v174, v144, v174
	v_med3_f32 v177, v177, s85, v226
	v_add_f32_e32 v175, v145, v175
	v_add_f32_e32 v168, v146, v168
	v_add_f32_e32 v169, 1.0, v169
	v_med3_f32 v174, v174, s85, v226
	v_mul_f32_e32 v177, 0xbfb8aa3b, v177
	v_med3_f32 v175, v175, s85, v226
	v_med3_f32 v166, v168, s85, v226
	v_add_f32_e32 v168, 1.0, v172
	v_rcp_f32_e32 v172, v169
	v_add_f32_e32 v169, v147, v178
	v_mul_f32_e32 v174, 0xbfb8aa3b, v174
	v_exp_f32_e32 v177, v177
	v_mul_f32_e32 v175, 0xbfb8aa3b, v175
	v_med3_f32 v167, v169, s85, v226
	v_add_f32_e32 v169, 1.0, v173
	v_add_f32_e32 v173, v135, v176
	v_add_f32_e32 v176, v148, v180
	v_exp_f32_e32 v178, v174
	v_add_f32_e32 v180, v149, v181
	v_exp_f32_e32 v181, v175
	v_med3_f32 v174, v176, s85, v226
	v_med3_f32 v180, v180, s85, v226
	v_mul_f32_e32 v166, 0xbfb8aa3b, v166
	v_mul_f32_e32 v167, 0xbfb8aa3b, v167
	v_mul_f32_e32 v174, 0xbfb8aa3b, v174
	v_add_f32_e32 v177, 1.0, v177
	v_mul_f32_e32 v175, 0xbfb8aa3b, v180
	v_exp_f32_e32 v166, v166
	v_exp_f32_e32 v167, v167
	v_exp_f32_e32 v174, v174
	v_add_f32_e32 v176, 1.0, v178
	v_exp_f32_e32 v175, v175
	v_rcp_f32_e32 v180, v177
	v_add_f32_e32 v177, 1.0, v181
	v_rcp_f32_e32 v168, v168
	v_rcp_f32_e32 v169, v169
	v_rcp_f32_e32 v176, v176
	v_rcp_f32_e32 v177, v177
	v_pk_add_f32 v[174:175], v[174:175], 1.0 op_sel_hi:[1,0]
	v_pk_add_f32 v[166:167], v[166:167], 1.0 op_sel_hi:[1,0]
	v_med3_f32 v173, v173, s85, v226
	v_pk_mul_f32 v[166:167], v[168:169], v[166:167]
	v_pk_mul_f32 v[168:169], v[176:177], v[174:175]
	v_mul_f32_e32 v173, 0xbfb8aa3b, v173
	v_pk_mul_f32 v[44:45], v[44:45], v[168:169]
	v_add_f32_e32 v169, v137, v179
	v_med3_f32 v169, v169, s85, v226
	v_mul_f32_e32 v169, 0xbfb8aa3b, v169
	v_exp_f32_e32 v173, v173
	v_exp_f32_e32 v169, v169
	v_add_f32_e32 v170, v138, v170
	v_add_f32_e32 v171, v139, v171
	v_add_f32_e32 v178, v140, v189
	v_add_f32_e32 v168, v141, v227
	v_med3_f32 v170, v170, s85, v226
	v_med3_f32 v171, v171, s85, v226
	v_med3_f32 v178, v178, s85, v226
	v_med3_f32 v168, v168, s85, v226
	v_mul_f32_e32 v170, 0xbfb8aa3b, v170
	v_mul_f32_e32 v171, 0xbfb8aa3b, v171
	v_mul_f32_e32 v178, 0xbfb8aa3b, v178
	v_mul_f32_e32 v168, 0xbfb8aa3b, v168
	v_exp_f32_e32 v170, v170
	v_exp_f32_e32 v171, v171
	v_add_f32_e32 v173, 1.0, v173
	v_exp_f32_e32 v178, v178
	v_exp_f32_e32 v179, v168
	v_pk_mul_f32 v[42:43], v[42:43], v[166:167]
	v_add_f32_e32 v166, 1.0, v169
	v_rcp_f32_e32 v173, v173
	v_rcp_f32_e32 v181, v166
	v_pk_add_f32 v[166:167], v[178:179], 1.0 op_sel_hi:[1,0]
	v_pk_add_f32 v[168:169], v[170:171], 1.0 op_sel_hi:[1,0]
	v_pk_mul_f32 v[166:167], v[180:181], v[166:167]
	v_pk_mul_f32 v[168:169], v[172:173], v[168:169]
	v_pk_mul_f32 v[40:41], v[40:41], v[166:167]
	v_pk_mul_f32 v[38:39], v[38:39], v[168:169]
	global_load_dwordx4 v[174:177], v[186:187], off offset:2048
	global_load_dwordx4 v[178:181], v[186:187], off offset:3072
	global_load_dwordx4 v[166:169], v[4:5], off offset:2048
	global_load_dwordx4 v[170:173], v[4:5], off offset:3072
	s_waitcnt vmcnt(7)
; #define UNPK0(q_) ((f32x4){bf_lo((q_).x), bf_hi((q_).x), bf_lo((q_).y), bf_hi((q_).y)})
; #define UNPK1(q_) ((f32x4){bf_lo((q_).z), bf_hi((q_).z), bf_lo((q_).w), bf_hi((q_).w)})
;     static __device__ __forceinline__ float eneg(float g) { return __builtin_amdgcn_exp2f(-1.4426950408889634f * fminf(fmaxf(g, -30.f), 30.f)); }
;     __device__ __forceinline__ void mid(f32x4 (&acc)[2][2][4][2], const Unit& u, int wr, int wc, int fr, int fq) const {
;     ...
;             for (int m = 2 * (am & 1); m < 2 * (am & 1) + 2; ++m) {
;                 pa.stage(ra[m][0], ra[m][1]); const u32x4 ga0 = pa.get(0), ga1 = pa.get(1);
;                 asm volatile("" ::: "memory");
;                 pb.stage(rb[m][0], rb[m][1]); const u32x4 gb0 = pb.get(0), gb1 = pb.get(1);
;                 asm volatile("" ::: "memory");
; #pragma unroll
;                 for (int bj = 0; bj < 2; ++bj) { const u32x4 ga = bj ? ga1 : ga0, gb = bj ? gb1 : gb0;
;                     const f32x4 a0 = UNPK0(ga) + ba[bj][0], a1 = UNPK1(ga) + ba[bj][1], b0 = UNPK0(gb) + bb[bj][0], b1 = UNPK1(gb) + bb[bj][1];
; #pragma unroll
;                     for (int k = 0; k < 4; ++k) { acc[ai][bj][m][0][k] *= (1.0f + eneg(b0[k])) * __builtin_amdgcn_rcpf(1.0f + eneg(a0[k]));
;                                                   acc[ai][bj][m][1][k] *= (1.0f + eneg(b1[k])) * __builtin_amdgcn_rcpf(1.0f + eneg(a1[k])); } } }
	ds_write_b128 v3, v[190:193]
	s_waitcnt vmcnt(6)
	ds_write_b128 v3, v[194:197] offset:1152
	ds_read_b128 v[190:193], v188
	ds_read_b128 v[194:197], v188 offset:64
	s_waitcnt vmcnt(5)
	ds_write_b128 v3, v[228:231]
	s_waitcnt vmcnt(4)
	ds_write_b128 v3, v[232:235] offset:1152
	ds_read_b128 v[228:231], v188
	ds_read_b128 v[232:235], v188 offset:64
	s_waitcnt lgkmcnt(5)
	v_lshlrev_b32_e32 v187, 16, v192
	v_lshlrev_b32_e32 v4, 16, v190
	v_add_f32_e32 v187, v150, v187
	v_add_f32_e32 v4, v158, v4
	v_med3_f32 v187, v187, s85, v226
	v_med3_f32 v4, v4, s85, v226
	v_mul_f32_e32 v187, 0xbfb8aa3b, v187
	v_mul_f32_e32 v4, 0xbfb8aa3b, v4
	v_exp_f32_e32 v187, v187
	v_and_b32_e32 v5, 0xffff0000, v190
	v_lshlrev_b32_e32 v189, 16, v191
	v_and_b32_e32 v227, 0xffff0000, v191
	v_and_b32_e32 v191, 0xffff0000, v192
	v_exp_f32_e32 v192, v4
	v_add_f32_e32 v5, v159, v5
	s_waitcnt lgkmcnt(1)
	v_lshlrev_b32_e32 v186, 16, v228
	v_med3_f32 v5, v5, s85, v226
	v_lshlrev_b32_e32 v236, 16, v193
	v_and_b32_e32 v237, 0xffff0000, v193
	v_and_b32_e32 v193, 0xffff0000, v228
	v_add_f32_e32 v186, v162, v186
	v_add_f32_e32 v187, 1.0, v187
	v_mul_f32_e32 v5, 0xbfb8aa3b, v5
	v_med3_f32 v4, v186, s85, v226
	v_add_f32_e32 v186, 1.0, v192
	v_rcp_f32_e32 v192, v187
	v_add_f32_e32 v187, v163, v193
	v_exp_f32_e32 v193, v5
	v_add_f32_e32 v189, v160, v189
	v_add_f32_e32 v191, v151, v191
	v_med3_f32 v189, v189, s85, v226
	v_med3_f32 v191, v191, s85, v226
	v_mul_f32_e32 v189, 0xbfb8aa3b, v189
	v_lshlrev_b32_e32 v190, 16, v230
	v_and_b32_e32 v230, 0xffff0000, v230
	v_mul_f32_e32 v191, 0xbfb8aa3b, v191
	v_exp_f32_e32 v189, v189
	v_lshlrev_b32_e32 v238, 16, v231
	v_and_b32_e32 v239, 0xffff0000, v231
	v_med3_f32 v5, v187, s85, v226
	v_add_f32_e32 v187, 1.0, v193
	v_add_f32_e32 v193, v155, v230
	v_exp_f32_e32 v230, v191
	v_add_f32_e32 v231, v152, v236
	v_med3_f32 v231, v231, s85, v226
	v_add_f32_e32 v227, v161, v227
	v_mul_f32_e32 v231, 0xbfb8aa3b, v231
	v_med3_f32 v227, v227, s85, v226
	v_add_f32_e32 v189, 1.0, v189
	v_exp_f32_e32 v231, v231
	v_mul_f32_e32 v227, 0xbfb8aa3b, v227
	v_lshlrev_b32_e32 v228, 16, v229
	v_and_b32_e32 v229, 0xffff0000, v229
	v_med3_f32 v191, v193, s85, v226
	v_add_f32_e32 v193, 1.0, v230
	v_rcp_f32_e32 v230, v189
	v_add_f32_e32 v189, v156, v238
	v_exp_f32_e32 v227, v227
	v_add_f32_e32 v228, v164, v228
	v_med3_f32 v189, v189, s85, v226
	v_add_f32_e32 v229, v165, v229
	v_med3_f32 v228, v228, s85, v226
	v_mul_f32_e32 v189, 0xbfb8aa3b, v189
	v_med3_f32 v229, v229, s85, v226
	v_mul_f32_e32 v4, 0xbfb8aa3b, v4
	v_mul_f32_e32 v5, 0xbfb8aa3b, v5
	v_mul_f32_e32 v228, 0xbfb8aa3b, v228
	v_exp_f32_e32 v236, v189
	v_add_f32_e32 v189, 1.0, v231
	v_mul_f32_e32 v229, 0xbfb8aa3b, v229
	v_exp_f32_e32 v4, v4
	v_exp_f32_e32 v5, v5
	v_exp_f32_e32 v228, v228
	v_exp_f32_e32 v229, v229
	v_rcp_f32_e32 v238, v189
	v_add_f32_e32 v189, 1.0, v227
	v_rcp_f32_e32 v186, v186
	v_rcp_f32_e32 v187, v187
	v_rcp_f32_e32 v231, v189
	v_pk_add_f32 v[228:229], v[228:229], 1.0 op_sel_hi:[1,0]
	v_pk_add_f32 v[4:5], v[4:5], 1.0 op_sel_hi:[1,0]
	v_add_f32_e32 v190, v154, v190
	v_pk_mul_f32 v[4:5], v[186:187], v[4:5]
	v_pk_mul_f32 v[186:187], v[230:231], v[228:229]
	v_med3_f32 v190, v190, s85, v226
	v_pk_mul_f32 v[36:37], v[36:37], v[186:187]
	v_add_f32_e32 v187, v153, v237
	v_med3_f32 v187, v187, s85, v226
	v_mul_f32_e32 v187, 0xbfb8aa3b, v187
	v_exp_f32_e32 v187, v187
	v_add_f32_e32 v186, v157, v239
	v_mul_f32_e32 v190, 0xbfb8aa3b, v190
	v_mul_f32_e32 v191, 0xbfb8aa3b, v191
	v_med3_f32 v186, v186, s85, v226
	v_exp_f32_e32 v190, v190
	v_exp_f32_e32 v191, v191
	v_mul_f32_e32 v186, 0xbfb8aa3b, v186
	v_rcp_f32_e32 v193, v193
	v_exp_f32_e32 v237, v186
	v_pk_mul_f32 v[34:35], v[34:35], v[4:5]
	v_add_f32_e32 v4, 1.0, v187
	v_rcp_f32_e32 v239, v4
	v_pk_add_f32 v[186:187], v[190:191], 1.0 op_sel_hi:[1,0]
	v_pk_add_f32 v[4:5], v[236:237], 1.0 op_sel_hi:[1,0]
	v_pk_mul_f32 v[186:187], v[192:193], v[186:187]
	v_pk_mul_f32 v[4:5], v[238:239], v[4:5]
	v_pk_mul_f32 v[30:31], v[30:31], v[186:187]
	v_lshlrev_b32_e32 v187, 16, v196
	v_pk_mul_f32 v[32:33], v[32:33], v[4:5]
	v_lshlrev_b32_e32 v4, 16, v194
	v_add_f32_e32 v187, v134, v187
	v_add_f32_e32 v4, v142, v4
	v_med3_f32 v187, v187, s85, v226
	v_med3_f32 v4, v4, s85, v226
	v_mul_f32_e32 v187, 0xbfb8aa3b, v187
	v_mul_f32_e32 v4, 0xbfb8aa3b, v4
	v_exp_f32_e32 v187, v187
	v_and_b32_e32 v5, 0xffff0000, v194
	v_exp_f32_e32 v192, v4
	v_add_f32_e32 v5, v143, v5
	s_waitcnt lgkmcnt(0)
	v_lshlrev_b32_e32 v186, 16, v232
	v_med3_f32 v5, v5, s85, v226
	v_lshlrev_b32_e32 v189, 16, v195
	v_and_b32_e32 v193, 0xffff0000, v232
	v_add_f32_e32 v186, v146, v186
	v_add_f32_e32 v187, 1.0, v187
	v_mul_f32_e32 v5, 0xbfb8aa3b, v5
	v_and_b32_e32 v191, 0xffff0000, v196
	v_med3_f32 v4, v186, s85, v226
	v_add_f32_e32 v186, 1.0, v192
	v_rcp_f32_e32 v192, v187
	v_add_f32_e32 v187, v147, v193
	v_exp_f32_e32 v193, v5
	v_add_f32_e32 v189, v144, v189
	v_add_f32_e32 v191, v135, v191
	v_med3_f32 v189, v189, s85, v226
	v_med3_f32 v191, v191, s85, v226
	v_mul_f32_e32 v189, 0xbfb8aa3b, v189
	v_lshlrev_b32_e32 v227, 16, v197
	v_and_b32_e32 v196, 0xffff0000, v234
	v_mul_f32_e32 v191, 0xbfb8aa3b, v191
	v_exp_f32_e32 v189, v189
	v_med3_f32 v5, v187, s85, v226
	v_add_f32_e32 v187, 1.0, v193
	v_add_f32_e32 v193, v139, v196
	v_exp_f32_e32 v196, v191
	v_add_f32_e32 v227, v136, v227
	v_med3_f32 v227, v227, s85, v226
	v_mul_f32_e32 v227, 0xbfb8aa3b, v227
	v_and_b32_e32 v195, 0xffff0000, v195
	v_lshlrev_b32_e32 v228, 16, v235
	v_add_f32_e32 v189, 1.0, v189
	v_exp_f32_e32 v227, v227
	v_med3_f32 v191, v193, s85, v226
	v_add_f32_e32 v193, 1.0, v196
	v_rcp_f32_e32 v196, v189
	v_add_f32_e32 v189, v140, v228
	v_add_f32_e32 v195, v145, v195
	v_med3_f32 v189, v189, s85, v226
	v_med3_f32 v195, v195, s85, v226
	v_mul_f32_e32 v189, 0xbfb8aa3b, v189
	v_mul_f32_e32 v195, 0xbfb8aa3b, v195
	v_and_b32_e32 v229, 0xffff0000, v197
	v_lshlrev_b32_e32 v194, 16, v233
	v_and_b32_e32 v197, 0xffff0000, v233
	v_exp_f32_e32 v228, v189
	v_add_f32_e32 v189, 1.0, v227
	v_exp_f32_e32 v227, v195
	v_add_f32_e32 v194, v148, v194
	v_add_f32_e32 v197, v149, v197
	v_med3_f32 v194, v194, s85, v226
	v_med3_f32 v197, v197, s85, v226
	v_mul_f32_e32 v4, 0xbfb8aa3b, v4
	v_mul_f32_e32 v5, 0xbfb8aa3b, v5
	v_mul_f32_e32 v194, 0xbfb8aa3b, v194
	v_mul_f32_e32 v195, 0xbfb8aa3b, v197
	v_exp_f32_e32 v4, v4
	v_exp_f32_e32 v5, v5
	v_exp_f32_e32 v194, v194
	v_exp_f32_e32 v195, v195
	v_rcp_f32_e32 v230, v189
	v_add_f32_e32 v189, 1.0, v227
	v_rcp_f32_e32 v186, v186
	v_rcp_f32_e32 v187, v187
	v_rcp_f32_e32 v197, v189
	v_pk_add_f32 v[194:195], v[194:195], 1.0 op_sel_hi:[1,0]
	v_pk_add_f32 v[4:5], v[4:5], 1.0 op_sel_hi:[1,0]
	v_lshlrev_b32_e32 v190, 16, v234
	v_pk_mul_f32 v[4:5], v[186:187], v[4:5]
	v_pk_mul_f32 v[186:187], v[196:197], v[194:195]
	s_waitcnt vmcnt(3)
; #define UNPK0(q_) ((f32x4){bf_lo((q_).x), bf_hi((q_).x), bf_lo((q_).y), bf_hi((q_).y)})
; #define UNPK1(q_) ((f32x4){bf_lo((q_).z), bf_hi((q_).z), bf_lo((q_).w), bf_hi((q_).w)})
;     static __device__ __forceinline__ float eneg(float g) { return __builtin_amdgcn_exp2f(-1.4426950408889634f * fminf(fmaxf(g, -30.f), 30.f)); }
;     __device__ __forceinline__ void mid(f32x4 (&acc)[2][2][4][2], const Unit& u, int wr, int wc, int fr, int fq) const {
;     ...
;             for (int m = 2 * (am & 1); m < 2 * (am & 1) + 2; ++m) {
;                 pa.stage(ra[m][0], ra[m][1]); const u32x4 ga0 = pa.get(0), ga1 = pa.get(1);
;                 asm volatile("" ::: "memory");
;                 pb.stage(rb[m][0], rb[m][1]); const u32x4 gb0 = pb.get(0), gb1 = pb.get(1);
;                 asm volatile("" ::: "memory");
; #pragma unroll
;                 for (int bj = 0; bj < 2; ++bj) { const u32x4 ga = bj ? ga1 : ga0, gb = bj ? gb1 : gb0;
;                     const f32x4 a0 = UNPK0(ga) + ba[bj][0], a1 = UNPK1(ga) + ba[bj][1], b0 = UNPK0(gb) + bb[bj][0], b1 = UNPK1(gb) + bb[bj][1];
; #pragma unroll
;                     for (int k = 0; k < 4; ++k) { acc[ai][bj][m][0][k] *= (1.0f + eneg(b0[k])) * __builtin_amdgcn_rcpf(1.0f + eneg(a0[k]));
;                                                   acc[ai][bj][m][1][k] *= (1.0f + eneg(b1[k])) * __builtin_amdgcn_rcpf(1.0f + eneg(a1[k])); } } }
	ds_write_b128 v3, v[174:177]
	s_waitcnt vmcnt(2)
	ds_write_b128 v3, v[178:181] offset:1152
	v_add_f32_e32 v190, v138, v190
	v_pk_mul_f32 v[28:29], v[28:29], v[186:187]
	v_add_f32_e32 v187, v137, v229
	ds_read_b128 v[174:177], v188
	ds_read_b128 v[178:181], v188 offset:64
	v_med3_f32 v190, v190, s85, v226
	v_med3_f32 v187, v187, s85, v226
	v_mul_f32_e32 v190, 0xbfb8aa3b, v190
	v_mul_f32_e32 v191, 0xbfb8aa3b, v191
	v_mul_f32_e32 v187, 0xbfb8aa3b, v187
	v_and_b32_e32 v231, 0xffff0000, v235
	v_exp_f32_e32 v190, v190
	v_exp_f32_e32 v191, v191
	v_exp_f32_e32 v187, v187
	v_rcp_f32_e32 v193, v193
	v_add_f32_e32 v186, v141, v231
	s_waitcnt vmcnt(1)
	ds_write_b128 v3, v[166:169]
	s_waitcnt vmcnt(0)
	ds_write_b128 v3, v[170:173] offset:1152
	s_waitcnt lgkmcnt(3)
	v_lshlrev_b32_e32 v3, 16, v174
	v_med3_f32 v186, v186, s85, v226
	v_add_f32_e32 v3, v158, v3
	v_mul_f32_e32 v186, 0xbfb8aa3b, v186
	v_med3_f32 v3, v3, s85, v226
	v_exp_f32_e32 v229, v186
	v_pk_mul_f32 v[26:27], v[26:27], v[4:5]
	v_add_f32_e32 v4, 1.0, v187
	v_pk_add_f32 v[186:187], v[190:191], 1.0 op_sel_hi:[1,0]
	v_mul_f32_e32 v3, 0xbfb8aa3b, v3
	v_rcp_f32_e32 v231, v4
	v_pk_mul_f32 v[186:187], v[192:193], v[186:187]
	ds_read_b128 v[166:169], v188
	ds_read_b128 v[170:173], v188 offset:64
	v_exp_f32_e32 v3, v3
	v_pk_mul_f32 v[22:23], v[22:23], v[186:187]
	v_lshlrev_b32_e32 v186, 16, v176
	v_add_f32_e32 v150, v150, v186
	v_pk_add_f32 v[4:5], v[228:229], 1.0 op_sel_hi:[1,0]
	v_med3_f32 v150, v150, s85, v226
	v_pk_mul_f32 v[4:5], v[230:231], v[4:5]
	s_waitcnt lgkmcnt(1)
	v_lshlrev_b32_e32 v189, 16, v168
	v_add_f32_e32 v3, 1.0, v3
	v_mul_f32_e32 v150, 0xbfb8aa3b, v150
	v_pk_mul_f32 v[24:25], v[24:25], v[4:5]
	v_and_b32_e32 v5, 0xffff0000, v174
	v_rcp_f32_e32 v158, v3
	v_add_f32_e32 v3, v154, v189
	v_exp_f32_e32 v154, v150
	v_add_f32_e32 v5, v159, v5
	v_med3_f32 v3, v3, s85, v226
	v_med3_f32 v5, v5, s85, v226
	v_mul_f32_e32 v3, 0xbfb8aa3b, v3
	v_mul_f32_e32 v5, 0xbfb8aa3b, v5
	v_lshlrev_b32_e32 v4, 16, v166
	v_and_b32_e32 v166, 0xffff0000, v166
	v_exp_f32_e32 v150, v3
	v_add_f32_e32 v3, 1.0, v154
	v_exp_f32_e32 v159, v5
	v_and_b32_e32 v176, 0xffff0000, v176
	v_rcp_f32_e32 v154, v3
	v_add_f32_e32 v3, v163, v166
	v_med3_f32 v3, v3, s85, v226
	v_add_f32_e32 v151, v151, v176
	v_mul_f32_e32 v3, 0xbfb8aa3b, v3
	v_med3_f32 v151, v151, s85, v226
	v_and_b32_e32 v168, 0xffff0000, v168
	v_exp_f32_e32 v5, v3
	v_add_f32_e32 v3, 1.0, v159
	v_mul_f32_e32 v151, 0xbfb8aa3b, v151
	v_lshlrev_b32_e32 v174, 16, v175
	v_rcp_f32_e32 v159, v3
	v_add_f32_e32 v3, v155, v168
	v_exp_f32_e32 v155, v151
	v_add_f32_e32 v160, v160, v174
	v_med3_f32 v3, v3, s85, v226
	v_med3_f32 v160, v160, s85, v226
	v_mul_f32_e32 v3, 0xbfb8aa3b, v3
	v_mul_f32_e32 v160, 0xbfb8aa3b, v160
	v_lshlrev_b32_e32 v188, 16, v167
	v_add_f32_e32 v4, v162, v4
	v_exp_f32_e32 v151, v3
	v_add_f32_e32 v3, 1.0, v155
	v_exp_f32_e32 v162, v160
	v_lshlrev_b32_e32 v187, 16, v177
	v_rcp_f32_e32 v155, v3
	v_add_f32_e32 v3, v164, v188
	v_med3_f32 v3, v3, s85, v226
	v_add_f32_e32 v152, v152, v187
	v_mul_f32_e32 v3, 0xbfb8aa3b, v3
	v_med3_f32 v152, v152, s85, v226
	v_and_b32_e32 v175, 0xffff0000, v175
	v_lshlrev_b32_e32 v190, 16, v169
	v_exp_f32_e32 v160, v3
	v_add_f32_e32 v3, 1.0, v162
	v_mul_f32_e32 v152, 0xbfb8aa3b, v152
	v_rcp_f32_e32 v162, v3
	v_add_f32_e32 v3, v156, v190
	v_exp_f32_e32 v156, v152
	v_add_f32_e32 v161, v161, v175
	v_med3_f32 v161, v161, s85, v226
	v_med3_f32 v3, v3, s85, v226
	v_mul_f32_e32 v161, 0xbfb8aa3b, v161
	v_and_b32_e32 v167, 0xffff0000, v167
	v_mul_f32_e32 v3, 0xbfb8aa3b, v3
	v_exp_f32_e32 v163, v161
	v_and_b32_e32 v177, 0xffff0000, v177
	v_exp_f32_e32 v152, v3
	v_add_f32_e32 v3, 1.0, v156
	v_add_f32_e32 v156, v165, v167
	v_med3_f32 v156, v156, s85, v226
	v_add_f32_e32 v153, v153, v177
	v_mul_f32_e32 v156, 0xbfb8aa3b, v156
	v_med3_f32 v153, v153, s85, v226
	v_and_b32_e32 v169, 0xffff0000, v169
	v_exp_f32_e32 v161, v156
	v_rcp_f32_e32 v156, v3
	v_add_f32_e32 v3, 1.0, v163
	v_mul_f32_e32 v153, 0xbfb8aa3b, v153
	v_rcp_f32_e32 v163, v3
	v_add_f32_e32 v3, v157, v169
	v_exp_f32_e32 v157, v153
	v_med3_f32 v4, v4, s85, v226
	v_med3_f32 v3, v3, s85, v226
	v_mul_f32_e32 v4, 0xbfb8aa3b, v4
	v_mul_f32_e32 v3, 0xbfb8aa3b, v3
	v_exp_f32_e32 v4, v4
	v_exp_f32_e32 v153, v3
	v_add_f32_e32 v3, 1.0, v157
	v_rcp_f32_e32 v157, v3
	v_lshlrev_b32_e32 v3, 16, v178
	v_add_f32_e32 v3, v142, v3
	v_med3_f32 v3, v3, s85, v226
	v_pk_add_f32 v[4:5], v[4:5], 1.0 op_sel_hi:[1,0]
	v_mul_f32_e32 v3, 0xbfb8aa3b, v3
	v_pk_mul_f32 v[4:5], v[158:159], v[4:5]
	v_exp_f32_e32 v3, v3
	v_pk_mul_f32 v[18:19], v[18:19], v[4:5]
	v_pk_add_f32 v[4:5], v[152:153], 1.0 op_sel_hi:[1,0]
	v_lshlrev_b32_e32 v152, 16, v180
	v_pk_add_f32 v[160:161], v[160:161], 1.0 op_sel_hi:[1,0]
	v_add_f32_e32 v134, v134, v152
	v_pk_mul_f32 v[158:159], v[162:163], v[160:161]
	v_med3_f32 v134, v134, s85, v226
	v_pk_mul_f32 v[20:21], v[20:21], v[158:159]
	v_pk_mul_f32 v[4:5], v[156:157], v[4:5]
	s_waitcnt lgkmcnt(0)
; #define UNPK0(q_) ((f32x4){bf_lo((q_).x), bf_hi((q_).x), bf_lo((q_).y), bf_hi((q_).y)})
; #define UNPK1(q_) ((f32x4){bf_lo((q_).z), bf_hi((q_).z), bf_lo((q_).w), bf_hi((q_).w)})
;     static __device__ __forceinline__ float eneg(float g) { return __builtin_amdgcn_exp2f(-1.4426950408889634f * fminf(fmaxf(g, -30.f), 30.f)); }
;     __device__ __forceinline__ void mid(f32x4 (&acc)[2][2][4][2], const Unit& u, int wr, int wc, int fr, int fq) const {
;     ...
;             for (int m = 2 * (am & 1); m < 2 * (am & 1) + 2; ++m) {
;                 pa.stage(ra[m][0], ra[m][1]); const u32x4 ga0 = pa.get(0), ga1 = pa.get(1);
;                 asm volatile("" ::: "memory");
;                 pb.stage(rb[m][0], rb[m][1]); const u32x4 gb0 = pb.get(0), gb1 = pb.get(1);
;                 asm volatile("" ::: "memory");
; #pragma unroll
;                 for (int bj = 0; bj < 2; ++bj) { const u32x4 ga = bj ? ga1 : ga0, gb = bj ? gb1 : gb0;
;                     const f32x4 a0 = UNPK0(ga) + ba[bj][0], a1 = UNPK1(ga) + ba[bj][1], b0 = UNPK0(gb) + bb[bj][0], b1 = UNPK1(gb) + bb[bj][1];
; #pragma unroll
;                     for (int k = 0; k < 4; ++k) { acc[ai][bj][m][0][k] *= (1.0f + eneg(b0[k])) * __builtin_amdgcn_rcpf(1.0f + eneg(a0[k]));
;                                                   acc[ai][bj][m][1][k] *= (1.0f + eneg(b1[k])) * __builtin_amdgcn_rcpf(1.0f + eneg(a1[k])); } } }
; template <class Epi, class Sched, bool ALIGN_EPI = false, bool SP2 = false>
; __device__ __forceinline__ void gemm_phase(PG8_LAS unsigned char* lds, const Gemm g, const Sched& S, const Epi& E) {
;     ...
;         for (int t = 0; t < nt; t += 2) {
;             if constexpr (Epi::HAS_MID) { if (t == (nt >> 1)) E.mid(acc, cur, wr, wc, fr, fq); }
	v_lshlrev_b32_e32 v159, 16, v172
	v_add_f32_e32 v3, 1.0, v3
	v_mul_f32_e32 v134, 0xbfb8aa3b, v134
	v_pk_mul_f32 v[16:17], v[16:17], v[4:5]
	v_and_b32_e32 v5, 0xffff0000, v178
	v_rcp_f32_e32 v142, v3
	v_add_f32_e32 v3, v138, v159
	v_exp_f32_e32 v138, v134
	v_add_f32_e32 v5, v143, v5
	v_med3_f32 v3, v3, s85, v226
	v_med3_f32 v5, v5, s85, v226
	v_mul_f32_e32 v3, 0xbfb8aa3b, v3
	v_mul_f32_e32 v5, 0xbfb8aa3b, v5
	v_and_b32_e32 v156, 0xffff0000, v170
	v_exp_f32_e32 v134, v3
	v_add_f32_e32 v3, 1.0, v138
	v_exp_f32_e32 v143, v5
	v_and_b32_e32 v153, 0xffff0000, v180
	v_rcp_f32_e32 v138, v3
	v_add_f32_e32 v3, v147, v156
	v_med3_f32 v3, v3, s85, v226
	v_add_f32_e32 v135, v135, v153
	v_pk_add_f32 v[150:151], v[150:151], 1.0 op_sel_hi:[1,0]
	v_mul_f32_e32 v3, 0xbfb8aa3b, v3
	v_med3_f32 v135, v135, s85, v226
	v_pk_mul_f32 v[150:151], v[154:155], v[150:151]
	v_and_b32_e32 v160, 0xffff0000, v172
	v_exp_f32_e32 v5, v3
	v_add_f32_e32 v3, 1.0, v143
	v_mul_f32_e32 v135, 0xbfb8aa3b, v135
	v_pk_mul_f32 v[14:15], v[14:15], v[150:151]
	v_lshlrev_b32_e32 v150, 16, v179
	v_rcp_f32_e32 v143, v3
	v_add_f32_e32 v3, v139, v160
	v_exp_f32_e32 v139, v135
	v_add_f32_e32 v144, v144, v150
	v_med3_f32 v3, v3, s85, v226
	v_med3_f32 v144, v144, s85, v226
	v_lshlrev_b32_e32 v4, 16, v170
	v_mul_f32_e32 v3, 0xbfb8aa3b, v3
	v_mul_f32_e32 v144, 0xbfb8aa3b, v144
	v_lshlrev_b32_e32 v157, 16, v171
	v_add_f32_e32 v4, v146, v4
	v_exp_f32_e32 v135, v3
	v_add_f32_e32 v3, 1.0, v139
	v_exp_f32_e32 v146, v144
	v_lshlrev_b32_e32 v154, 16, v181
	v_rcp_f32_e32 v139, v3
	v_add_f32_e32 v3, v148, v157
	v_med3_f32 v3, v3, s85, v226
	v_add_f32_e32 v136, v136, v154
	v_mul_f32_e32 v3, 0xbfb8aa3b, v3
	v_med3_f32 v136, v136, s85, v226
	v_and_b32_e32 v151, 0xffff0000, v179
	v_lshlrev_b32_e32 v161, 16, v173
	v_exp_f32_e32 v144, v3
	v_add_f32_e32 v3, 1.0, v146
	v_mul_f32_e32 v136, 0xbfb8aa3b, v136
	v_rcp_f32_e32 v146, v3
	v_add_f32_e32 v3, v140, v161
	v_exp_f32_e32 v140, v136
	v_add_f32_e32 v145, v145, v151
	v_med3_f32 v145, v145, s85, v226
	v_med3_f32 v3, v3, s85, v226
	v_mul_f32_e32 v145, 0xbfb8aa3b, v145
	v_and_b32_e32 v158, 0xffff0000, v171
	v_mul_f32_e32 v3, 0xbfb8aa3b, v3
	v_exp_f32_e32 v147, v145
	v_and_b32_e32 v155, 0xffff0000, v181
	v_exp_f32_e32 v136, v3
	v_add_f32_e32 v3, 1.0, v140
	v_add_f32_e32 v140, v149, v158
	v_med3_f32 v140, v140, s85, v226
	v_add_f32_e32 v137, v137, v155
	v_mul_f32_e32 v140, 0xbfb8aa3b, v140
	v_med3_f32 v137, v137, s85, v226
	v_and_b32_e32 v162, 0xffff0000, v173
	v_exp_f32_e32 v145, v140
	v_rcp_f32_e32 v140, v3
	v_add_f32_e32 v3, 1.0, v147
	v_mul_f32_e32 v137, 0xbfb8aa3b, v137
	v_med3_f32 v4, v4, s85, v226
	v_rcp_f32_e32 v147, v3
	v_add_f32_e32 v3, v141, v162
	v_exp_f32_e32 v141, v137
	v_mul_f32_e32 v4, 0xbfb8aa3b, v4
	v_exp_f32_e32 v4, v4
	v_med3_f32 v3, v3, s85, v226
	v_mul_f32_e32 v3, 0xbfb8aa3b, v3
	v_exp_f32_e32 v137, v3
	v_add_f32_e32 v3, 1.0, v141
	v_rcp_f32_e32 v141, v3
	v_pk_add_f32 v[4:5], v[4:5], 1.0 op_sel_hi:[1,0]
	v_pk_add_f32 v[144:145], v[144:145], 1.0 op_sel_hi:[1,0]
	v_pk_mul_f32 v[4:5], v[142:143], v[4:5]
	v_pk_add_f32 v[134:135], v[134:135], 1.0 op_sel_hi:[1,0]
	v_pk_mul_f32 v[10:11], v[10:11], v[4:5]
	v_pk_add_f32 v[4:5], v[136:137], 1.0 op_sel_hi:[1,0]
	v_pk_mul_f32 v[142:143], v[146:147], v[144:145]
	v_pk_mul_f32 v[134:135], v[138:139], v[134:135]
	v_pk_mul_f32 v[4:5], v[140:141], v[4:5]
	v_pk_mul_f32 v[12:13], v[12:13], v[142:143]
	v_pk_mul_f32 v[8:9], v[8:9], v[4:5]
	v_pk_mul_f32 v[6:7], v[6:7], v[134:135]
	s_bitcmp1_b32 s10, 0
	s_cbranch_scc0 .Lp3_mid_noy
	s_barrier
.Lp3_mid_noy:
	s_branch .LBB0_380
.LBB0_383:
	s_and_b64 vcc, exec, s[14:15]
	s_cbranch_vccz .LBB0_385
	s_barrier
